# GEMM loops (UP, OUT/DOWN, INA, FINAL): LDS-DMA loads use SGPR base + 32-bit VGPR offset; 64-bit VALU address adds replaced by scalar adds
# speedup vs baseline: 1.0193x; 1.0080x over previous
.LBB0_252:
	s_add_u32 s0, s0, 0x80
	s_addc_u32 s1, s1, 0
	s_add_u32 s47, s4, 0x100
	s_addc_u32 s48, s5, 0
	s_mov_b32 s4, 0
	s_waitcnt lgkmcnt(0)
	s_waitcnt vmcnt(0)
	s_add_i32 s49, s4, 2
	s_add_u32 s16, s0, 0x80
	s_addc_u32 s5, s1, 0
	s_add_i32 s65, 0, 0x10000
	v_add_u32_e32 v142, s65, v145
	ds_read_b128 v[148:151], v142
	ds_read_b128 v[152:155], v142 offset:1024
	ds_read_b128 v[156:159], v142 offset:2048
	ds_read_b128 v[160:163], v142 offset:3072
	s_cmp_eq_u32 s41, s4
	s_cselect_b32 s4, s10, s16
	s_cselect_b32 s5, s11, s5
	s_cselect_b32 s17, s13, s48
	s_cselect_b32 s16, s12, s47
	v_lshl_add_u64 v[142:143], s[0:1], 0, v[138:139]
	s_add_i32 m0, s26, 0xc000
	ds_read_b128 v[164:167], v146
	ds_read_b128 v[168:171], v146 offset:1024
	ds_read_b128 v[172:175], v146 offset:2048
	ds_read_b128 v[176:179], v146 offset:3072
	ds_read_b128 v[180:183], v146 offset:4096
	ds_read_b128 v[204:207], v146 offset:5120
	ds_read_b128 v[208:211], v146 offset:6144
	ds_read_b128 v[212:215], v146 offset:7168
	global_load_lds_dwordx4 v[142:143], off
	v_lshl_add_u64 v[142:143], s[0:1], 0, v[140:141]
	s_add_i32 m0, s26, 0xe000
	s_nop 0
	global_load_lds_dwordx4 v[142:143], off
	s_waitcnt lgkmcnt(8)
	s_barrier
	s_waitcnt lgkmcnt(0)
	v_mfma_f32_16x16x32_bf16 v[126:129], v[148:151], v[164:167], 0
	v_mfma_f32_16x16x32_bf16 v[122:125], v[156:159], v[164:167], 0
	v_mfma_f32_16x16x32_bf16 v[110:113], v[148:151], v[172:175], 0
	v_mfma_f32_16x16x32_bf16 v[106:109], v[156:159], v[172:175], 0
	v_mfma_f32_16x16x32_bf16 v[94:97], v[148:151], v[180:183], 0
	v_mfma_f32_16x16x32_bf16 v[90:93], v[156:159], v[180:183], 0
	v_mfma_f32_16x16x32_bf16 v[78:81], v[148:151], v[208:211], 0
	v_mfma_f32_16x16x32_bf16 v[74:77], v[156:159], v[208:211], 0
	v_mfma_f32_16x16x32_bf16 v[126:129], v[152:155], v[168:171], v[126:129]
	v_mfma_f32_16x16x32_bf16 v[122:125], v[160:163], v[168:171], v[122:125]
	v_mfma_f32_16x16x32_bf16 v[110:113], v[152:155], v[176:179], v[110:113]
	v_mfma_f32_16x16x32_bf16 v[106:109], v[160:163], v[176:179], v[106:109]
	v_mfma_f32_16x16x32_bf16 v[94:97], v[152:155], v[204:207], v[94:97]
	v_mfma_f32_16x16x32_bf16 v[90:93], v[160:163], v[204:207], v[90:93]
	v_mfma_f32_16x16x32_bf16 v[78:81], v[152:155], v[212:215], v[78:81]
	v_mfma_f32_16x16x32_bf16 v[74:77], v[160:163], v[212:215], v[74:77]
	s_barrier
	s_add_i32 s66, 0, 0x14000
	v_add_u32_e32 v142, s66, v145
	s_add_i32 s65, s65, s24
	ds_read_b128 v[216:219], v142
	ds_read_b128 v[220:223], v142 offset:1024
	ds_read_b128 v[224:227], v142 offset:2048
	ds_read_b128 v[228:231], v142 offset:3072
	s_add_u32 s70, s16, s6
	s_addc_u32 s71, s17, s7
	s_mov_b32 m0, s65
	s_nop 0
	global_load_lds_dwordx4 v132, s[16:17]
	s_add_i32 m0, s65, 0x2000
	s_nop 0
	global_load_lds_dwordx4 v136, s[16:17]
	s_barrier
	s_waitcnt lgkmcnt(0)
	v_mfma_f32_16x16x32_bf16 v[114:117], v[216:219], v[164:167], 0
	v_mfma_f32_16x16x32_bf16 v[118:121], v[224:227], v[164:167], 0
	v_mfma_f32_16x16x32_bf16 v[98:101], v[216:219], v[172:175], 0
	v_mfma_f32_16x16x32_bf16 v[102:105], v[224:227], v[172:175], 0
	v_mfma_f32_16x16x32_bf16 v[82:85], v[216:219], v[180:183], 0
	v_mfma_f32_16x16x32_bf16 v[86:89], v[224:227], v[180:183], 0
	v_mfma_f32_16x16x32_bf16 v[66:69], v[216:219], v[208:211], 0
	v_mfma_f32_16x16x32_bf16 v[70:73], v[224:227], v[208:211], 0
	v_mfma_f32_16x16x32_bf16 v[114:117], v[220:223], v[168:171], v[114:117]
	v_mfma_f32_16x16x32_bf16 v[118:121], v[228:231], v[168:171], v[118:121]
	v_mfma_f32_16x16x32_bf16 v[98:101], v[220:223], v[176:179], v[98:101]
	v_mfma_f32_16x16x32_bf16 v[102:105], v[228:231], v[176:179], v[102:105]
	v_mfma_f32_16x16x32_bf16 v[82:85], v[220:223], v[204:207], v[82:85]
	v_mfma_f32_16x16x32_bf16 v[86:89], v[228:231], v[204:207], v[86:89]
	v_mfma_f32_16x16x32_bf16 v[66:69], v[220:223], v[212:215], v[66:69]
	v_mfma_f32_16x16x32_bf16 v[70:73], v[228:231], v[212:215], v[70:73]
	s_barrier
	s_mov_b32 m0, s26
	s_add_u32 s72, s4, s6
	s_addc_u32 s73, s5, s7
	ds_read_b128 v[164:167], v146 offset:16384
	ds_read_b128 v[168:171], v146 offset:17408
	ds_read_b128 v[172:175], v146 offset:18432
	ds_read_b128 v[176:179], v146 offset:19456
	ds_read_b128 v[180:183], v146 offset:20480
	ds_read_b128 v[204:207], v146 offset:21504
	ds_read_b128 v[208:211], v146 offset:22528
	ds_read_b128 v[212:215], v146 offset:23552
	global_load_lds_dwordx4 v130, s[4:5]
	s_mov_b32 m0, s27
	s_nop 0
	global_load_lds_dwordx4 v134, s[4:5]
	s_barrier
	s_waitcnt lgkmcnt(0)
	v_mfma_f32_16x16x32_bf16 v[62:65], v[148:151], v[164:167], 0
	v_mfma_f32_16x16x32_bf16 v[58:61], v[156:159], v[164:167], 0
	v_mfma_f32_16x16x32_bf16 v[46:49], v[148:151], v[172:175], 0
	v_mfma_f32_16x16x32_bf16 v[42:45], v[156:159], v[172:175], 0
	v_mfma_f32_16x16x32_bf16 v[30:33], v[148:151], v[180:183], 0
	v_mfma_f32_16x16x32_bf16 v[26:29], v[156:159], v[180:183], 0
	v_mfma_f32_16x16x32_bf16 v[14:17], v[148:151], v[208:211], 0
	v_mfma_f32_16x16x32_bf16 v[10:13], v[156:159], v[208:211], 0
	v_mfma_f32_16x16x32_bf16 v[62:65], v[152:155], v[168:171], v[62:65]
	v_mfma_f32_16x16x32_bf16 v[58:61], v[160:163], v[168:171], v[58:61]
	v_mfma_f32_16x16x32_bf16 v[46:49], v[152:155], v[176:179], v[46:49]
	v_mfma_f32_16x16x32_bf16 v[42:45], v[160:163], v[176:179], v[42:45]
	v_mfma_f32_16x16x32_bf16 v[30:33], v[152:155], v[204:207], v[30:33]
	v_mfma_f32_16x16x32_bf16 v[26:29], v[160:163], v[204:207], v[26:29]
	v_mfma_f32_16x16x32_bf16 v[14:17], v[152:155], v[212:215], v[14:17]
	v_mfma_f32_16x16x32_bf16 v[10:13], v[160:163], v[212:215], v[10:13]
	s_barrier
	s_add_u32 s16, s16, s92
	s_addc_u32 s17, s17, 0
	s_add_i32 s65, s66, s24
	s_add_u32 s76, s16, s6
	s_addc_u32 s77, s17, s7
	s_mov_b32 m0, s65
	s_nop 0
	global_load_lds_dwordx4 v132, s[16:17]
	s_add_i32 m0, s65, 0x2000
	s_nop 0
	global_load_lds_dwordx4 v136, s[16:17]
	s_waitcnt vmcnt(6)
	s_barrier
	v_mfma_f32_16x16x32_bf16 v[50:53], v[216:219], v[164:167], 0
	v_mfma_f32_16x16x32_bf16 v[54:57], v[224:227], v[164:167], 0
	v_mfma_f32_16x16x32_bf16 v[34:37], v[216:219], v[172:175], 0
	v_mfma_f32_16x16x32_bf16 v[38:41], v[224:227], v[172:175], 0
	v_mfma_f32_16x16x32_bf16 v[18:21], v[216:219], v[180:183], 0
	v_mfma_f32_16x16x32_bf16 v[22:25], v[224:227], v[180:183], 0
	v_mfma_f32_16x16x32_bf16 v[6:9], v[216:219], v[208:211], 0
	v_mfma_f32_16x16x32_bf16 v[2:5], v[224:227], v[208:211], 0
	v_mfma_f32_16x16x32_bf16 v[50:53], v[220:223], v[168:171], v[50:53]
	v_mfma_f32_16x16x32_bf16 v[54:57], v[228:231], v[168:171], v[54:57]
	v_mfma_f32_16x16x32_bf16 v[34:37], v[220:223], v[176:179], v[34:37]
	v_mfma_f32_16x16x32_bf16 v[38:41], v[228:231], v[176:179], v[38:41]
	v_mfma_f32_16x16x32_bf16 v[18:21], v[220:223], v[204:207], v[18:21]
	v_mfma_f32_16x16x32_bf16 v[22:25], v[228:231], v[204:207], v[22:25]
	v_mfma_f32_16x16x32_bf16 v[6:9], v[220:223], v[212:215], v[6:9]
	v_mfma_f32_16x16x32_bf16 v[2:5], v[228:231], v[212:215], v[2:5]
	s_barrier
	s_add_i32 s16, 0, 0x18000
	v_add_u32_e32 v147, s16, v145
	ds_read_b128 v[148:151], v147
	ds_read_b128 v[152:155], v147 offset:1024
	ds_read_b128 v[156:159], v147 offset:2048
	ds_read_b128 v[160:163], v147 offset:3072
	s_add_u32 s4, s4, s92
	s_addc_u32 s5, s5, 0
	s_mov_b32 m0, s28
	ds_read_b128 v[164:167], v146 offset:32768
	ds_read_b128 v[168:171], v146 offset:33792
	ds_read_b128 v[172:175], v146 offset:34816
	ds_read_b128 v[176:179], v146 offset:35840
	ds_read_b128 v[180:183], v146 offset:36864
	ds_read_b128 v[204:207], v146 offset:37888
	ds_read_b128 v[208:211], v146 offset:38912
	ds_read_b128 v[212:215], v146 offset:39936
	global_load_lds_dwordx4 v130, s[4:5]
	s_mov_b32 m0, s29
	s_nop 0
	global_load_lds_dwordx4 v134, s[4:5]
	s_waitcnt lgkmcnt(8)
	s_barrier
	s_waitcnt lgkmcnt(0)
	v_mfma_f32_16x16x32_bf16 v[126:129], v[148:151], v[164:167], v[126:129]
	v_mfma_f32_16x16x32_bf16 v[122:125], v[156:159], v[164:167], v[122:125]
	v_mfma_f32_16x16x32_bf16 v[110:113], v[148:151], v[172:175], v[110:113]
	v_mfma_f32_16x16x32_bf16 v[106:109], v[156:159], v[172:175], v[106:109]
	v_mfma_f32_16x16x32_bf16 v[94:97], v[148:151], v[180:183], v[94:97]
	v_mfma_f32_16x16x32_bf16 v[90:93], v[156:159], v[180:183], v[90:93]
	v_mfma_f32_16x16x32_bf16 v[78:81], v[148:151], v[208:211], v[78:81]
	v_mfma_f32_16x16x32_bf16 v[74:77], v[156:159], v[208:211], v[74:77]
	v_mfma_f32_16x16x32_bf16 v[126:129], v[152:155], v[168:171], v[126:129]
	v_mfma_f32_16x16x32_bf16 v[122:125], v[160:163], v[168:171], v[122:125]
	v_mfma_f32_16x16x32_bf16 v[110:113], v[152:155], v[176:179], v[110:113]
	v_mfma_f32_16x16x32_bf16 v[106:109], v[160:163], v[176:179], v[106:109]
	v_mfma_f32_16x16x32_bf16 v[94:97], v[152:155], v[204:207], v[94:97]
	v_mfma_f32_16x16x32_bf16 v[90:93], v[160:163], v[204:207], v[90:93]
	v_mfma_f32_16x16x32_bf16 v[78:81], v[152:155], v[212:215], v[78:81]
	v_mfma_f32_16x16x32_bf16 v[74:77], v[160:163], v[212:215], v[74:77]
	s_barrier
	s_add_i32 s4, 0, 0x1c000
	s_add_i32 s5, s16, s24
	v_add_u32_e32 v147, s4, v145
	s_mov_b32 m0, s5
	ds_read_b128 v[216:219], v147
	ds_read_b128 v[220:223], v147 offset:1024
	ds_read_b128 v[224:227], v147 offset:2048
	ds_read_b128 v[228:231], v147 offset:3072
	global_load_lds_dwordx4 v132, s[70:71]
	s_add_i32 m0, s5, 0x2000
	s_nop 0
	global_load_lds_dwordx4 v136, s[70:71]
	s_barrier
	s_waitcnt lgkmcnt(0)
	v_mfma_f32_16x16x32_bf16 v[114:117], v[216:219], v[164:167], v[114:117]
	v_mfma_f32_16x16x32_bf16 v[118:121], v[224:227], v[164:167], v[118:121]
	v_mfma_f32_16x16x32_bf16 v[98:101], v[216:219], v[172:175], v[98:101]
	v_mfma_f32_16x16x32_bf16 v[102:105], v[224:227], v[172:175], v[102:105]
	v_mfma_f32_16x16x32_bf16 v[82:85], v[216:219], v[180:183], v[82:85]
	v_mfma_f32_16x16x32_bf16 v[86:89], v[224:227], v[180:183], v[86:89]
	v_mfma_f32_16x16x32_bf16 v[66:69], v[216:219], v[208:211], v[66:69]
	v_mfma_f32_16x16x32_bf16 v[70:73], v[224:227], v[208:211], v[70:73]
	v_mfma_f32_16x16x32_bf16 v[114:117], v[220:223], v[168:171], v[114:117]
	v_mfma_f32_16x16x32_bf16 v[118:121], v[228:231], v[168:171], v[118:121]
	v_mfma_f32_16x16x32_bf16 v[98:101], v[220:223], v[176:179], v[98:101]
	v_mfma_f32_16x16x32_bf16 v[102:105], v[228:231], v[176:179], v[102:105]
	v_mfma_f32_16x16x32_bf16 v[82:85], v[220:223], v[204:207], v[82:85]
	v_mfma_f32_16x16x32_bf16 v[86:89], v[228:231], v[204:207], v[86:89]
	v_mfma_f32_16x16x32_bf16 v[66:69], v[220:223], v[212:215], v[66:69]
	v_mfma_f32_16x16x32_bf16 v[70:73], v[228:231], v[212:215], v[70:73]
	s_barrier
	s_mov_b32 m0, s35
	ds_read_b128 v[164:167], v146 offset:49152
	ds_read_b128 v[168:171], v146 offset:50176
	ds_read_b128 v[172:175], v146 offset:51200
	ds_read_b128 v[176:179], v146 offset:52224
	ds_read_b128 v[180:183], v146 offset:53248
	ds_read_b128 v[204:207], v146 offset:54272
	ds_read_b128 v[208:211], v146 offset:55296
	ds_read_b128 v[212:215], v146 offset:56320
	global_load_lds_dwordx4 v130, s[72:73]
	s_mov_b32 m0, s40
	s_nop 0
	global_load_lds_dwordx4 v134, s[72:73]
	s_barrier
	s_waitcnt lgkmcnt(0)
	v_mfma_f32_16x16x32_bf16 v[62:65], v[148:151], v[164:167], v[62:65]
	v_mfma_f32_16x16x32_bf16 v[58:61], v[156:159], v[164:167], v[58:61]
	v_mfma_f32_16x16x32_bf16 v[46:49], v[148:151], v[172:175], v[46:49]
	v_mfma_f32_16x16x32_bf16 v[42:45], v[156:159], v[172:175], v[42:45]
	v_mfma_f32_16x16x32_bf16 v[30:33], v[148:151], v[180:183], v[30:33]
	v_mfma_f32_16x16x32_bf16 v[26:29], v[156:159], v[180:183], v[26:29]
	v_mfma_f32_16x16x32_bf16 v[14:17], v[148:151], v[208:211], v[14:17]
	v_mfma_f32_16x16x32_bf16 v[10:13], v[156:159], v[208:211], v[10:13]
	v_mfma_f32_16x16x32_bf16 v[62:65], v[152:155], v[168:171], v[62:65]
	v_mfma_f32_16x16x32_bf16 v[58:61], v[160:163], v[168:171], v[58:61]
	v_mfma_f32_16x16x32_bf16 v[46:49], v[152:155], v[176:179], v[46:49]
	v_mfma_f32_16x16x32_bf16 v[42:45], v[160:163], v[176:179], v[42:45]
	v_mfma_f32_16x16x32_bf16 v[30:33], v[152:155], v[204:207], v[30:33]
	v_mfma_f32_16x16x32_bf16 v[26:29], v[160:163], v[204:207], v[26:29]
	v_mfma_f32_16x16x32_bf16 v[14:17], v[152:155], v[212:215], v[14:17]
	v_mfma_f32_16x16x32_bf16 v[10:13], v[160:163], v[212:215], v[10:13]
	s_barrier
	s_add_i32 s4, s4, s24
	s_mov_b32 m0, s4
	s_nop 0
	global_load_lds_dwordx4 v132, s[76:77]
	s_add_i32 m0, s4, 0x2000
	s_nop 0
	global_load_lds_dwordx4 v136, s[76:77]
	s_add_u32 s0, s0, 0x100
	s_addc_u32 s1, s1, 0
	s_add_u32 s47, s47, 0x100
	s_addc_u32 s48, s48, 0
	s_cmp_ge_u32 s49, s30
	s_mov_b32 s4, s49
	s_waitcnt vmcnt(6)
	s_barrier
	v_mfma_f32_16x16x32_bf16 v[50:53], v[216:219], v[164:167], v[50:53]
	v_mfma_f32_16x16x32_bf16 v[54:57], v[224:227], v[164:167], v[54:57]
	v_mfma_f32_16x16x32_bf16 v[34:37], v[216:219], v[172:175], v[34:37]
	v_mfma_f32_16x16x32_bf16 v[38:41], v[224:227], v[172:175], v[38:41]
	v_mfma_f32_16x16x32_bf16 v[18:21], v[216:219], v[180:183], v[18:21]
	v_mfma_f32_16x16x32_bf16 v[22:25], v[224:227], v[180:183], v[22:25]
	v_mfma_f32_16x16x32_bf16 v[6:9], v[216:219], v[208:211], v[6:9]
	v_mfma_f32_16x16x32_bf16 v[2:5], v[224:227], v[208:211], v[2:5]
	v_mfma_f32_16x16x32_bf16 v[50:53], v[220:223], v[168:171], v[50:53]
	v_mfma_f32_16x16x32_bf16 v[54:57], v[228:231], v[168:171], v[54:57]
	v_mfma_f32_16x16x32_bf16 v[34:37], v[220:223], v[176:179], v[34:37]
	v_mfma_f32_16x16x32_bf16 v[38:41], v[228:231], v[176:179], v[38:41]
	v_mfma_f32_16x16x32_bf16 v[18:21], v[220:223], v[204:207], v[18:21]
	v_mfma_f32_16x16x32_bf16 v[22:25], v[228:231], v[204:207], v[22:25]
	v_mfma_f32_16x16x32_bf16 v[6:9], v[220:223], v[212:215], v[6:9]
	v_mfma_f32_16x16x32_bf16 v[2:5], v[228:231], v[212:215], v[2:5]
	s_barrier
	s_cbranch_scc1 .Lkexit_253
.LBB0_253:
	s_add_i32 s49, s4, 2
	s_add_u32 s16, s0, 0x80
	s_addc_u32 s5, s1, 0
	s_add_i32 s65, 0, 0x10000
	v_add_u32_e32 v142, s65, v145
	ds_read_b128 v[148:151], v142
	ds_read_b128 v[152:155], v142 offset:1024
	ds_read_b128 v[156:159], v142 offset:2048
	ds_read_b128 v[160:163], v142 offset:3072
	s_cmp_eq_u32 s41, s4
	s_cselect_b32 s4, s10, s16
	s_cselect_b32 s5, s11, s5
	s_cselect_b32 s17, s13, s48
	s_cselect_b32 s16, s12, s47
	v_lshl_add_u64 v[142:143], s[0:1], 0, v[138:139]
	s_add_i32 m0, s26, 0xc000
	ds_read_b128 v[164:167], v146
	ds_read_b128 v[168:171], v146 offset:1024
	ds_read_b128 v[172:175], v146 offset:2048
	ds_read_b128 v[176:179], v146 offset:3072
	ds_read_b128 v[180:183], v146 offset:4096
	ds_read_b128 v[204:207], v146 offset:5120
	ds_read_b128 v[208:211], v146 offset:6144
	ds_read_b128 v[212:215], v146 offset:7168
	global_load_lds_dwordx4 v[142:143], off
	v_lshl_add_u64 v[142:143], s[0:1], 0, v[140:141]
	s_add_i32 m0, s26, 0xe000
	s_nop 0
	global_load_lds_dwordx4 v[142:143], off
	s_waitcnt lgkmcnt(8)
	s_barrier
	s_waitcnt lgkmcnt(0)
	v_mfma_f32_16x16x32_bf16 v[126:129], v[148:151], v[164:167], v[126:129]
	v_mfma_f32_16x16x32_bf16 v[122:125], v[156:159], v[164:167], v[122:125]
	v_mfma_f32_16x16x32_bf16 v[110:113], v[148:151], v[172:175], v[110:113]
	v_mfma_f32_16x16x32_bf16 v[106:109], v[156:159], v[172:175], v[106:109]
	v_mfma_f32_16x16x32_bf16 v[94:97], v[148:151], v[180:183], v[94:97]
	v_mfma_f32_16x16x32_bf16 v[90:93], v[156:159], v[180:183], v[90:93]
	v_mfma_f32_16x16x32_bf16 v[78:81], v[148:151], v[208:211], v[78:81]
	v_mfma_f32_16x16x32_bf16 v[74:77], v[156:159], v[208:211], v[74:77]
	v_mfma_f32_16x16x32_bf16 v[126:129], v[152:155], v[168:171], v[126:129]
	v_mfma_f32_16x16x32_bf16 v[122:125], v[160:163], v[168:171], v[122:125]
	v_mfma_f32_16x16x32_bf16 v[110:113], v[152:155], v[176:179], v[110:113]
	v_mfma_f32_16x16x32_bf16 v[106:109], v[160:163], v[176:179], v[106:109]
	v_mfma_f32_16x16x32_bf16 v[94:97], v[152:155], v[204:207], v[94:97]
	v_mfma_f32_16x16x32_bf16 v[90:93], v[160:163], v[204:207], v[90:93]
	v_mfma_f32_16x16x32_bf16 v[78:81], v[152:155], v[212:215], v[78:81]
	v_mfma_f32_16x16x32_bf16 v[74:77], v[160:163], v[212:215], v[74:77]
	s_barrier
	s_add_i32 s66, 0, 0x14000
	v_add_u32_e32 v142, s66, v145
	s_add_i32 s65, s65, s24
	ds_read_b128 v[216:219], v142
	ds_read_b128 v[220:223], v142 offset:1024
	ds_read_b128 v[224:227], v142 offset:2048
	ds_read_b128 v[228:231], v142 offset:3072
	s_add_u32 s70, s16, s6
	s_addc_u32 s71, s17, s7
	s_mov_b32 m0, s65
	s_nop 0
	global_load_lds_dwordx4 v132, s[16:17]
	s_add_i32 m0, s65, 0x2000
	s_nop 0
	global_load_lds_dwordx4 v136, s[16:17]
	s_barrier
	s_waitcnt lgkmcnt(0)
	v_mfma_f32_16x16x32_bf16 v[114:117], v[216:219], v[164:167], v[114:117]
	v_mfma_f32_16x16x32_bf16 v[118:121], v[224:227], v[164:167], v[118:121]
	v_mfma_f32_16x16x32_bf16 v[98:101], v[216:219], v[172:175], v[98:101]
	v_mfma_f32_16x16x32_bf16 v[102:105], v[224:227], v[172:175], v[102:105]
	v_mfma_f32_16x16x32_bf16 v[82:85], v[216:219], v[180:183], v[82:85]
	v_mfma_f32_16x16x32_bf16 v[86:89], v[224:227], v[180:183], v[86:89]
	v_mfma_f32_16x16x32_bf16 v[66:69], v[216:219], v[208:211], v[66:69]
	v_mfma_f32_16x16x32_bf16 v[70:73], v[224:227], v[208:211], v[70:73]
	v_mfma_f32_16x16x32_bf16 v[114:117], v[220:223], v[168:171], v[114:117]
	v_mfma_f32_16x16x32_bf16 v[118:121], v[228:231], v[168:171], v[118:121]
	v_mfma_f32_16x16x32_bf16 v[98:101], v[220:223], v[176:179], v[98:101]
	v_mfma_f32_16x16x32_bf16 v[102:105], v[228:231], v[176:179], v[102:105]
	v_mfma_f32_16x16x32_bf16 v[82:85], v[220:223], v[204:207], v[82:85]
	v_mfma_f32_16x16x32_bf16 v[86:89], v[228:231], v[204:207], v[86:89]
	v_mfma_f32_16x16x32_bf16 v[66:69], v[220:223], v[212:215], v[66:69]
	v_mfma_f32_16x16x32_bf16 v[70:73], v[228:231], v[212:215], v[70:73]
	s_barrier
	s_mov_b32 m0, s26
	s_add_u32 s72, s4, s6
	s_addc_u32 s73, s5, s7
	ds_read_b128 v[164:167], v146 offset:16384
	ds_read_b128 v[168:171], v146 offset:17408
	ds_read_b128 v[172:175], v146 offset:18432
	ds_read_b128 v[176:179], v146 offset:19456
	ds_read_b128 v[180:183], v146 offset:20480
	ds_read_b128 v[204:207], v146 offset:21504
	ds_read_b128 v[208:211], v146 offset:22528
	ds_read_b128 v[212:215], v146 offset:23552
	global_load_lds_dwordx4 v130, s[4:5]
	s_mov_b32 m0, s27
	s_nop 0
	global_load_lds_dwordx4 v134, s[4:5]
	s_barrier
	s_waitcnt lgkmcnt(0)
	v_mfma_f32_16x16x32_bf16 v[62:65], v[148:151], v[164:167], v[62:65]
	v_mfma_f32_16x16x32_bf16 v[58:61], v[156:159], v[164:167], v[58:61]
	v_mfma_f32_16x16x32_bf16 v[46:49], v[148:151], v[172:175], v[46:49]
	v_mfma_f32_16x16x32_bf16 v[42:45], v[156:159], v[172:175], v[42:45]
	v_mfma_f32_16x16x32_bf16 v[30:33], v[148:151], v[180:183], v[30:33]
	v_mfma_f32_16x16x32_bf16 v[26:29], v[156:159], v[180:183], v[26:29]
	v_mfma_f32_16x16x32_bf16 v[14:17], v[148:151], v[208:211], v[14:17]
	v_mfma_f32_16x16x32_bf16 v[10:13], v[156:159], v[208:211], v[10:13]
	v_mfma_f32_16x16x32_bf16 v[62:65], v[152:155], v[168:171], v[62:65]
	v_mfma_f32_16x16x32_bf16 v[58:61], v[160:163], v[168:171], v[58:61]
	v_mfma_f32_16x16x32_bf16 v[46:49], v[152:155], v[176:179], v[46:49]
	v_mfma_f32_16x16x32_bf16 v[42:45], v[160:163], v[176:179], v[42:45]
	v_mfma_f32_16x16x32_bf16 v[30:33], v[152:155], v[204:207], v[30:33]
	v_mfma_f32_16x16x32_bf16 v[26:29], v[160:163], v[204:207], v[26:29]
	v_mfma_f32_16x16x32_bf16 v[14:17], v[152:155], v[212:215], v[14:17]
	v_mfma_f32_16x16x32_bf16 v[10:13], v[160:163], v[212:215], v[10:13]
	s_barrier
	s_add_u32 s16, s16, s92
	s_addc_u32 s17, s17, 0
	s_add_i32 s65, s66, s24
	s_add_u32 s76, s16, s6
	s_addc_u32 s77, s17, s7
	s_mov_b32 m0, s65
	s_nop 0
	global_load_lds_dwordx4 v132, s[16:17]
	s_add_i32 m0, s65, 0x2000
	s_nop 0
	global_load_lds_dwordx4 v136, s[16:17]
	s_waitcnt vmcnt(6)
	s_barrier
	v_mfma_f32_16x16x32_bf16 v[50:53], v[216:219], v[164:167], v[50:53]
	v_mfma_f32_16x16x32_bf16 v[54:57], v[224:227], v[164:167], v[54:57]
	v_mfma_f32_16x16x32_bf16 v[34:37], v[216:219], v[172:175], v[34:37]
	v_mfma_f32_16x16x32_bf16 v[38:41], v[224:227], v[172:175], v[38:41]
	v_mfma_f32_16x16x32_bf16 v[18:21], v[216:219], v[180:183], v[18:21]
	v_mfma_f32_16x16x32_bf16 v[22:25], v[224:227], v[180:183], v[22:25]
	v_mfma_f32_16x16x32_bf16 v[6:9], v[216:219], v[208:211], v[6:9]
	v_mfma_f32_16x16x32_bf16 v[2:5], v[224:227], v[208:211], v[2:5]
	v_mfma_f32_16x16x32_bf16 v[50:53], v[220:223], v[168:171], v[50:53]
	v_mfma_f32_16x16x32_bf16 v[54:57], v[228:231], v[168:171], v[54:57]
	v_mfma_f32_16x16x32_bf16 v[34:37], v[220:223], v[176:179], v[34:37]
	v_mfma_f32_16x16x32_bf16 v[38:41], v[228:231], v[176:179], v[38:41]
	v_mfma_f32_16x16x32_bf16 v[18:21], v[220:223], v[204:207], v[18:21]
	v_mfma_f32_16x16x32_bf16 v[22:25], v[228:231], v[204:207], v[22:25]
	v_mfma_f32_16x16x32_bf16 v[6:9], v[220:223], v[212:215], v[6:9]
	v_mfma_f32_16x16x32_bf16 v[2:5], v[228:231], v[212:215], v[2:5]
	s_barrier
	s_add_i32 s16, 0, 0x18000
	v_add_u32_e32 v147, s16, v145
	ds_read_b128 v[148:151], v147
	ds_read_b128 v[152:155], v147 offset:1024
	ds_read_b128 v[156:159], v147 offset:2048
	ds_read_b128 v[160:163], v147 offset:3072
	s_add_u32 s4, s4, s92
	s_addc_u32 s5, s5, 0
	s_mov_b32 m0, s28
	ds_read_b128 v[164:167], v146 offset:32768
	ds_read_b128 v[168:171], v146 offset:33792
	ds_read_b128 v[172:175], v146 offset:34816
	ds_read_b128 v[176:179], v146 offset:35840
	ds_read_b128 v[180:183], v146 offset:36864
	ds_read_b128 v[204:207], v146 offset:37888
	ds_read_b128 v[208:211], v146 offset:38912
	ds_read_b128 v[212:215], v146 offset:39936
	global_load_lds_dwordx4 v130, s[4:5]
	s_mov_b32 m0, s29
	s_nop 0
	global_load_lds_dwordx4 v134, s[4:5]
	s_waitcnt lgkmcnt(8)
	s_barrier
	s_waitcnt lgkmcnt(0)
	v_mfma_f32_16x16x32_bf16 v[126:129], v[148:151], v[164:167], v[126:129]
	v_mfma_f32_16x16x32_bf16 v[122:125], v[156:159], v[164:167], v[122:125]
	v_mfma_f32_16x16x32_bf16 v[110:113], v[148:151], v[172:175], v[110:113]
	v_mfma_f32_16x16x32_bf16 v[106:109], v[156:159], v[172:175], v[106:109]
	v_mfma_f32_16x16x32_bf16 v[94:97], v[148:151], v[180:183], v[94:97]
	v_mfma_f32_16x16x32_bf16 v[90:93], v[156:159], v[180:183], v[90:93]
	v_mfma_f32_16x16x32_bf16 v[78:81], v[148:151], v[208:211], v[78:81]
	v_mfma_f32_16x16x32_bf16 v[74:77], v[156:159], v[208:211], v[74:77]
	v_mfma_f32_16x16x32_bf16 v[126:129], v[152:155], v[168:171], v[126:129]
	v_mfma_f32_16x16x32_bf16 v[122:125], v[160:163], v[168:171], v[122:125]
	v_mfma_f32_16x16x32_bf16 v[110:113], v[152:155], v[176:179], v[110:113]
	v_mfma_f32_16x16x32_bf16 v[106:109], v[160:163], v[176:179], v[106:109]
	v_mfma_f32_16x16x32_bf16 v[94:97], v[152:155], v[204:207], v[94:97]
	v_mfma_f32_16x16x32_bf16 v[90:93], v[160:163], v[204:207], v[90:93]
	v_mfma_f32_16x16x32_bf16 v[78:81], v[152:155], v[212:215], v[78:81]
	v_mfma_f32_16x16x32_bf16 v[74:77], v[160:163], v[212:215], v[74:77]
	s_barrier
	s_add_i32 s4, 0, 0x1c000
	s_add_i32 s5, s16, s24
	v_add_u32_e32 v147, s4, v145
	s_mov_b32 m0, s5
	ds_read_b128 v[216:219], v147
	ds_read_b128 v[220:223], v147 offset:1024
	ds_read_b128 v[224:227], v147 offset:2048
	ds_read_b128 v[228:231], v147 offset:3072
	global_load_lds_dwordx4 v132, s[70:71]
	s_add_i32 m0, s5, 0x2000
	s_nop 0
	global_load_lds_dwordx4 v136, s[70:71]
	s_barrier
	s_waitcnt lgkmcnt(0)
	v_mfma_f32_16x16x32_bf16 v[114:117], v[216:219], v[164:167], v[114:117]
	v_mfma_f32_16x16x32_bf16 v[118:121], v[224:227], v[164:167], v[118:121]
	v_mfma_f32_16x16x32_bf16 v[98:101], v[216:219], v[172:175], v[98:101]
	v_mfma_f32_16x16x32_bf16 v[102:105], v[224:227], v[172:175], v[102:105]
	v_mfma_f32_16x16x32_bf16 v[82:85], v[216:219], v[180:183], v[82:85]
	v_mfma_f32_16x16x32_bf16 v[86:89], v[224:227], v[180:183], v[86:89]
	v_mfma_f32_16x16x32_bf16 v[66:69], v[216:219], v[208:211], v[66:69]
	v_mfma_f32_16x16x32_bf16 v[70:73], v[224:227], v[208:211], v[70:73]
	v_mfma_f32_16x16x32_bf16 v[114:117], v[220:223], v[168:171], v[114:117]
	v_mfma_f32_16x16x32_bf16 v[118:121], v[228:231], v[168:171], v[118:121]
	v_mfma_f32_16x16x32_bf16 v[98:101], v[220:223], v[176:179], v[98:101]
	v_mfma_f32_16x16x32_bf16 v[102:105], v[228:231], v[176:179], v[102:105]
	v_mfma_f32_16x16x32_bf16 v[82:85], v[220:223], v[204:207], v[82:85]
	v_mfma_f32_16x16x32_bf16 v[86:89], v[228:231], v[204:207], v[86:89]
	v_mfma_f32_16x16x32_bf16 v[66:69], v[220:223], v[212:215], v[66:69]
	v_mfma_f32_16x16x32_bf16 v[70:73], v[228:231], v[212:215], v[70:73]
	s_barrier
	s_mov_b32 m0, s35
	ds_read_b128 v[164:167], v146 offset:49152
	ds_read_b128 v[168:171], v146 offset:50176
	ds_read_b128 v[172:175], v146 offset:51200
	ds_read_b128 v[176:179], v146 offset:52224
	ds_read_b128 v[180:183], v146 offset:53248
	ds_read_b128 v[204:207], v146 offset:54272
	ds_read_b128 v[208:211], v146 offset:55296
	ds_read_b128 v[212:215], v146 offset:56320
	global_load_lds_dwordx4 v130, s[72:73]
	s_mov_b32 m0, s40
	s_nop 0
	global_load_lds_dwordx4 v134, s[72:73]
	s_barrier
	s_waitcnt lgkmcnt(0)
	v_mfma_f32_16x16x32_bf16 v[62:65], v[148:151], v[164:167], v[62:65]
	v_mfma_f32_16x16x32_bf16 v[58:61], v[156:159], v[164:167], v[58:61]
	v_mfma_f32_16x16x32_bf16 v[46:49], v[148:151], v[172:175], v[46:49]
	v_mfma_f32_16x16x32_bf16 v[42:45], v[156:159], v[172:175], v[42:45]
	v_mfma_f32_16x16x32_bf16 v[30:33], v[148:151], v[180:183], v[30:33]
	v_mfma_f32_16x16x32_bf16 v[26:29], v[156:159], v[180:183], v[26:29]
	v_mfma_f32_16x16x32_bf16 v[14:17], v[148:151], v[208:211], v[14:17]
	v_mfma_f32_16x16x32_bf16 v[10:13], v[156:159], v[208:211], v[10:13]
	v_mfma_f32_16x16x32_bf16 v[62:65], v[152:155], v[168:171], v[62:65]
	v_mfma_f32_16x16x32_bf16 v[58:61], v[160:163], v[168:171], v[58:61]
	v_mfma_f32_16x16x32_bf16 v[46:49], v[152:155], v[176:179], v[46:49]
	v_mfma_f32_16x16x32_bf16 v[42:45], v[160:163], v[176:179], v[42:45]
	v_mfma_f32_16x16x32_bf16 v[30:33], v[152:155], v[204:207], v[30:33]
	v_mfma_f32_16x16x32_bf16 v[26:29], v[160:163], v[204:207], v[26:29]
	v_mfma_f32_16x16x32_bf16 v[14:17], v[152:155], v[212:215], v[14:17]
	v_mfma_f32_16x16x32_bf16 v[10:13], v[160:163], v[212:215], v[10:13]
	s_barrier
	s_add_i32 s4, s4, s24
	s_mov_b32 m0, s4
	s_nop 0
	global_load_lds_dwordx4 v132, s[76:77]
	s_add_i32 m0, s4, 0x2000
	s_nop 0
	global_load_lds_dwordx4 v136, s[76:77]
	s_add_u32 s0, s0, 0x100
	s_addc_u32 s1, s1, 0
	s_add_u32 s47, s47, 0x100
	s_addc_u32 s48, s48, 0
	s_cmp_ge_u32 s49, s30
	s_mov_b32 s4, s49
	s_waitcnt vmcnt(6)
	s_barrier
	v_mfma_f32_16x16x32_bf16 v[50:53], v[216:219], v[164:167], v[50:53]
	v_mfma_f32_16x16x32_bf16 v[54:57], v[224:227], v[164:167], v[54:57]
	v_mfma_f32_16x16x32_bf16 v[34:37], v[216:219], v[172:175], v[34:37]
	v_mfma_f32_16x16x32_bf16 v[38:41], v[224:227], v[172:175], v[38:41]
	v_mfma_f32_16x16x32_bf16 v[18:21], v[216:219], v[180:183], v[18:21]
	v_mfma_f32_16x16x32_bf16 v[22:25], v[224:227], v[180:183], v[22:25]
	v_mfma_f32_16x16x32_bf16 v[6:9], v[216:219], v[208:211], v[6:9]
	v_mfma_f32_16x16x32_bf16 v[2:5], v[224:227], v[208:211], v[2:5]
	v_mfma_f32_16x16x32_bf16 v[50:53], v[220:223], v[168:171], v[50:53]
	v_mfma_f32_16x16x32_bf16 v[54:57], v[228:231], v[168:171], v[54:57]
	v_mfma_f32_16x16x32_bf16 v[34:37], v[220:223], v[176:179], v[34:37]
	v_mfma_f32_16x16x32_bf16 v[38:41], v[228:231], v[176:179], v[38:41]
	v_mfma_f32_16x16x32_bf16 v[18:21], v[220:223], v[204:207], v[18:21]
	v_mfma_f32_16x16x32_bf16 v[22:25], v[228:231], v[204:207], v[22:25]
	v_mfma_f32_16x16x32_bf16 v[6:9], v[220:223], v[212:215], v[6:9]
	v_mfma_f32_16x16x32_bf16 v[2:5], v[228:231], v[212:215], v[2:5]
	s_barrier
	s_cbranch_scc0 .LBB0_253

.LBB0_663:
	s_add_u32 s0, s0, 0x80
	s_addc_u32 s1, s1, 0
	s_add_u32 s49, s4, 0x100
	s_addc_u32 s65, s5, 0
	s_mov_b32 s4, 0
	s_waitcnt lgkmcnt(0)
	s_waitcnt vmcnt(0)
	s_add_i32 s66, s4, 2
	s_add_u32 s18, s0, 0x80
	s_addc_u32 s5, s1, 0
	s_add_i32 s68, 0, 0x10000
	v_add_u32_e32 v150, s68, v153
	ds_read_b128 v[142:145], v150
	ds_read_b128 v[146:149], v150 offset:1024
	ds_read_b128 v[156:159], v150 offset:2048
	ds_read_b128 v[160:163], v150 offset:3072
	s_cmp_eq_u32 s43, s4
	s_cselect_b32 s4, s10, s18
	s_cselect_b32 s5, s11, s5
	s_cselect_b32 s19, s13, s65
	s_cselect_b32 s18, s12, s49
	v_lshl_add_u64 v[150:151], s[0:1], 0, v[138:139]
	s_add_i32 m0, s28, 0xc000
	ds_read_b128 v[164:167], v154
	ds_read_b128 v[168:171], v154 offset:1024
	ds_read_b128 v[172:175], v154 offset:2048
	ds_read_b128 v[176:179], v154 offset:3072
	ds_read_b128 v[180:183], v154 offset:4096
	ds_read_b128 v[204:207], v154 offset:5120
	ds_read_b128 v[208:211], v154 offset:6144
	ds_read_b128 v[212:215], v154 offset:7168
	global_load_lds_dwordx4 v[150:151], off
	v_lshl_add_u64 v[150:151], s[0:1], 0, v[140:141]
	s_add_i32 m0, s28, 0xe000
	s_nop 0
	global_load_lds_dwordx4 v[150:151], off
	s_waitcnt lgkmcnt(8)
	s_barrier
	s_waitcnt lgkmcnt(0)
	v_mfma_f32_16x16x32_bf16 v[126:129], v[142:145], v[164:167], 0
	v_mfma_f32_16x16x32_bf16 v[122:125], v[156:159], v[164:167], 0
	v_mfma_f32_16x16x32_bf16 v[110:113], v[142:145], v[172:175], 0
	v_mfma_f32_16x16x32_bf16 v[106:109], v[156:159], v[172:175], 0
	v_mfma_f32_16x16x32_bf16 v[94:97], v[142:145], v[180:183], 0
	v_mfma_f32_16x16x32_bf16 v[90:93], v[156:159], v[180:183], 0
	v_mfma_f32_16x16x32_bf16 v[78:81], v[142:145], v[208:211], 0
	v_mfma_f32_16x16x32_bf16 v[74:77], v[156:159], v[208:211], 0
	v_mfma_f32_16x16x32_bf16 v[126:129], v[146:149], v[168:171], v[126:129]
	v_mfma_f32_16x16x32_bf16 v[122:125], v[160:163], v[168:171], v[122:125]
	v_mfma_f32_16x16x32_bf16 v[110:113], v[146:149], v[176:179], v[110:113]
	v_mfma_f32_16x16x32_bf16 v[106:109], v[160:163], v[176:179], v[106:109]
	v_mfma_f32_16x16x32_bf16 v[94:97], v[146:149], v[204:207], v[94:97]
	v_mfma_f32_16x16x32_bf16 v[90:93], v[160:163], v[204:207], v[90:93]
	v_mfma_f32_16x16x32_bf16 v[78:81], v[146:149], v[212:215], v[78:81]
	v_mfma_f32_16x16x32_bf16 v[74:77], v[160:163], v[212:215], v[74:77]
	s_barrier
	s_add_i32 s69, 0, 0x14000
	v_add_u32_e32 v150, s69, v153
	s_add_i32 s68, s68, s25
	ds_read_b128 v[216:219], v150
	ds_read_b128 v[220:223], v150 offset:1024
	ds_read_b128 v[224:227], v150 offset:2048
	ds_read_b128 v[228:231], v150 offset:3072
	s_add_u32 s70, s18, s6
	s_addc_u32 s71, s19, s7
	s_mov_b32 m0, s68
	s_nop 0
	global_load_lds_dwordx4 v132, s[18:19]
	s_add_i32 m0, s68, 0x2000
	s_nop 0
	global_load_lds_dwordx4 v136, s[18:19]
	s_barrier
	s_waitcnt lgkmcnt(0)
	v_mfma_f32_16x16x32_bf16 v[118:121], v[216:219], v[164:167], 0
	v_mfma_f32_16x16x32_bf16 v[114:117], v[224:227], v[164:167], 0
	v_mfma_f32_16x16x32_bf16 v[102:105], v[216:219], v[172:175], 0
	v_mfma_f32_16x16x32_bf16 v[98:101], v[224:227], v[172:175], 0
	v_mfma_f32_16x16x32_bf16 v[86:89], v[216:219], v[180:183], 0
	v_mfma_f32_16x16x32_bf16 v[82:85], v[224:227], v[180:183], 0
	v_mfma_f32_16x16x32_bf16 v[70:73], v[216:219], v[208:211], 0
	v_mfma_f32_16x16x32_bf16 v[66:69], v[224:227], v[208:211], 0
	v_mfma_f32_16x16x32_bf16 v[118:121], v[220:223], v[168:171], v[118:121]
	v_mfma_f32_16x16x32_bf16 v[114:117], v[228:231], v[168:171], v[114:117]
	v_mfma_f32_16x16x32_bf16 v[102:105], v[220:223], v[176:179], v[102:105]
	v_mfma_f32_16x16x32_bf16 v[98:101], v[228:231], v[176:179], v[98:101]
	v_mfma_f32_16x16x32_bf16 v[86:89], v[220:223], v[204:207], v[86:89]
	v_mfma_f32_16x16x32_bf16 v[82:85], v[228:231], v[204:207], v[82:85]
	v_mfma_f32_16x16x32_bf16 v[70:73], v[220:223], v[212:215], v[70:73]
	v_mfma_f32_16x16x32_bf16 v[66:69], v[228:231], v[212:215], v[66:69]
	s_barrier
	s_mov_b32 m0, s28
	s_add_u32 s72, s4, s6
	s_addc_u32 s73, s5, s7
	ds_read_b128 v[164:167], v154 offset:16384
	ds_read_b128 v[168:171], v154 offset:17408
	ds_read_b128 v[172:175], v154 offset:18432
	ds_read_b128 v[176:179], v154 offset:19456
	ds_read_b128 v[180:183], v154 offset:20480
	ds_read_b128 v[204:207], v154 offset:21504
	ds_read_b128 v[208:211], v154 offset:22528
	ds_read_b128 v[212:215], v154 offset:23552
	global_load_lds_dwordx4 v130, s[4:5]
	s_mov_b32 m0, s29
	s_nop 0
	global_load_lds_dwordx4 v134, s[4:5]
	s_barrier
	s_waitcnt lgkmcnt(0)
	v_mfma_f32_16x16x32_bf16 v[62:65], v[142:145], v[164:167], 0
	v_mfma_f32_16x16x32_bf16 v[58:61], v[156:159], v[164:167], 0
	v_mfma_f32_16x16x32_bf16 v[46:49], v[142:145], v[172:175], 0
	v_mfma_f32_16x16x32_bf16 v[42:45], v[156:159], v[172:175], 0
	v_mfma_f32_16x16x32_bf16 v[30:33], v[142:145], v[180:183], 0
	v_mfma_f32_16x16x32_bf16 v[26:29], v[156:159], v[180:183], 0
	v_mfma_f32_16x16x32_bf16 v[14:17], v[142:145], v[208:211], 0
	v_mfma_f32_16x16x32_bf16 v[10:13], v[156:159], v[208:211], 0
	v_mfma_f32_16x16x32_bf16 v[62:65], v[146:149], v[168:171], v[62:65]
	v_mfma_f32_16x16x32_bf16 v[58:61], v[160:163], v[168:171], v[58:61]
	v_mfma_f32_16x16x32_bf16 v[46:49], v[146:149], v[176:179], v[46:49]
	v_mfma_f32_16x16x32_bf16 v[42:45], v[160:163], v[176:179], v[42:45]
	v_mfma_f32_16x16x32_bf16 v[30:33], v[146:149], v[204:207], v[30:33]
	v_mfma_f32_16x16x32_bf16 v[26:29], v[160:163], v[204:207], v[26:29]
	v_mfma_f32_16x16x32_bf16 v[14:17], v[146:149], v[212:215], v[14:17]
	v_mfma_f32_16x16x32_bf16 v[10:13], v[160:163], v[212:215], v[10:13]
	s_barrier
	s_add_u32 s18, s18, s14
	s_addc_u32 s19, s19, 0
	s_add_i32 s68, s69, s25
	s_add_u32 s76, s18, s6
	s_addc_u32 s77, s19, s7
	s_mov_b32 m0, s68
	s_nop 0
	global_load_lds_dwordx4 v132, s[18:19]
	s_add_i32 m0, s68, 0x2000
	s_nop 0
	global_load_lds_dwordx4 v136, s[18:19]
	s_waitcnt vmcnt(6)
	s_barrier
	v_mfma_f32_16x16x32_bf16 v[54:57], v[216:219], v[164:167], 0
	v_mfma_f32_16x16x32_bf16 v[50:53], v[224:227], v[164:167], 0
	v_mfma_f32_16x16x32_bf16 v[38:41], v[216:219], v[172:175], 0
	v_mfma_f32_16x16x32_bf16 v[34:37], v[224:227], v[172:175], 0
	v_mfma_f32_16x16x32_bf16 v[22:25], v[216:219], v[180:183], 0
	v_mfma_f32_16x16x32_bf16 v[18:21], v[224:227], v[180:183], 0
	v_mfma_f32_16x16x32_bf16 v[6:9], v[216:219], v[208:211], 0
	v_mfma_f32_16x16x32_bf16 v[2:5], v[224:227], v[208:211], 0
	v_mfma_f32_16x16x32_bf16 v[54:57], v[220:223], v[168:171], v[54:57]
	v_mfma_f32_16x16x32_bf16 v[50:53], v[228:231], v[168:171], v[50:53]
	v_mfma_f32_16x16x32_bf16 v[38:41], v[220:223], v[176:179], v[38:41]
	v_mfma_f32_16x16x32_bf16 v[34:37], v[228:231], v[176:179], v[34:37]
	v_mfma_f32_16x16x32_bf16 v[22:25], v[220:223], v[204:207], v[22:25]
	v_mfma_f32_16x16x32_bf16 v[18:21], v[228:231], v[204:207], v[18:21]
	v_mfma_f32_16x16x32_bf16 v[6:9], v[220:223], v[212:215], v[6:9]
	v_mfma_f32_16x16x32_bf16 v[2:5], v[228:231], v[212:215], v[2:5]
	s_barrier
	s_add_i32 s18, 0, 0x18000
	v_add_u32_e32 v155, s18, v153
	ds_read_b128 v[142:145], v155
	ds_read_b128 v[146:149], v155 offset:1024
	ds_read_b128 v[156:159], v155 offset:2048
	ds_read_b128 v[160:163], v155 offset:3072
	s_add_u32 s4, s4, s14
	s_addc_u32 s5, s5, 0
	s_mov_b32 m0, s31
	ds_read_b128 v[164:167], v154 offset:32768
	ds_read_b128 v[168:171], v154 offset:33792
	ds_read_b128 v[172:175], v154 offset:34816
	ds_read_b128 v[176:179], v154 offset:35840
	ds_read_b128 v[180:183], v154 offset:36864
	ds_read_b128 v[204:207], v154 offset:37888
	ds_read_b128 v[208:211], v154 offset:38912
	ds_read_b128 v[212:215], v154 offset:39936
	global_load_lds_dwordx4 v130, s[4:5]
	s_mov_b32 m0, s34
	s_nop 0
	global_load_lds_dwordx4 v134, s[4:5]
	s_waitcnt lgkmcnt(8)
	s_barrier
	s_waitcnt lgkmcnt(0)
	v_mfma_f32_16x16x32_bf16 v[126:129], v[142:145], v[164:167], v[126:129]
	v_mfma_f32_16x16x32_bf16 v[122:125], v[156:159], v[164:167], v[122:125]
	v_mfma_f32_16x16x32_bf16 v[110:113], v[142:145], v[172:175], v[110:113]
	v_mfma_f32_16x16x32_bf16 v[106:109], v[156:159], v[172:175], v[106:109]
	v_mfma_f32_16x16x32_bf16 v[94:97], v[142:145], v[180:183], v[94:97]
	v_mfma_f32_16x16x32_bf16 v[90:93], v[156:159], v[180:183], v[90:93]
	v_mfma_f32_16x16x32_bf16 v[78:81], v[142:145], v[208:211], v[78:81]
	v_mfma_f32_16x16x32_bf16 v[74:77], v[156:159], v[208:211], v[74:77]
	v_mfma_f32_16x16x32_bf16 v[126:129], v[146:149], v[168:171], v[126:129]
	v_mfma_f32_16x16x32_bf16 v[122:125], v[160:163], v[168:171], v[122:125]
	v_mfma_f32_16x16x32_bf16 v[110:113], v[146:149], v[176:179], v[110:113]
	v_mfma_f32_16x16x32_bf16 v[106:109], v[160:163], v[176:179], v[106:109]
	v_mfma_f32_16x16x32_bf16 v[94:97], v[146:149], v[204:207], v[94:97]
	v_mfma_f32_16x16x32_bf16 v[90:93], v[160:163], v[204:207], v[90:93]
	v_mfma_f32_16x16x32_bf16 v[78:81], v[146:149], v[212:215], v[78:81]
	v_mfma_f32_16x16x32_bf16 v[74:77], v[160:163], v[212:215], v[74:77]
	s_barrier
	s_add_i32 s4, 0, 0x1c000
	s_add_i32 s5, s18, s25
	v_add_u32_e32 v155, s4, v153
	s_mov_b32 m0, s5
	ds_read_b128 v[216:219], v155
	ds_read_b128 v[220:223], v155 offset:1024
	ds_read_b128 v[224:227], v155 offset:2048
	ds_read_b128 v[228:231], v155 offset:3072
	global_load_lds_dwordx4 v132, s[70:71]
	s_add_i32 m0, s5, 0x2000
	s_nop 0
	global_load_lds_dwordx4 v136, s[70:71]
	s_barrier
	s_waitcnt lgkmcnt(0)
	v_mfma_f32_16x16x32_bf16 v[118:121], v[216:219], v[164:167], v[118:121]
	v_mfma_f32_16x16x32_bf16 v[114:117], v[224:227], v[164:167], v[114:117]
	v_mfma_f32_16x16x32_bf16 v[102:105], v[216:219], v[172:175], v[102:105]
	v_mfma_f32_16x16x32_bf16 v[98:101], v[224:227], v[172:175], v[98:101]
	v_mfma_f32_16x16x32_bf16 v[86:89], v[216:219], v[180:183], v[86:89]
	v_mfma_f32_16x16x32_bf16 v[82:85], v[224:227], v[180:183], v[82:85]
	v_mfma_f32_16x16x32_bf16 v[70:73], v[216:219], v[208:211], v[70:73]
	v_mfma_f32_16x16x32_bf16 v[66:69], v[224:227], v[208:211], v[66:69]
	v_mfma_f32_16x16x32_bf16 v[118:121], v[220:223], v[168:171], v[118:121]
	v_mfma_f32_16x16x32_bf16 v[114:117], v[228:231], v[168:171], v[114:117]
	v_mfma_f32_16x16x32_bf16 v[102:105], v[220:223], v[176:179], v[102:105]
	v_mfma_f32_16x16x32_bf16 v[98:101], v[228:231], v[176:179], v[98:101]
	v_mfma_f32_16x16x32_bf16 v[86:89], v[220:223], v[204:207], v[86:89]
	v_mfma_f32_16x16x32_bf16 v[82:85], v[228:231], v[204:207], v[82:85]
	v_mfma_f32_16x16x32_bf16 v[70:73], v[220:223], v[212:215], v[70:73]
	v_mfma_f32_16x16x32_bf16 v[66:69], v[228:231], v[212:215], v[66:69]
	s_barrier
	s_mov_b32 m0, s41
	ds_read_b128 v[164:167], v154 offset:49152
	ds_read_b128 v[168:171], v154 offset:50176
	ds_read_b128 v[172:175], v154 offset:51200
	ds_read_b128 v[176:179], v154 offset:52224
	ds_read_b128 v[180:183], v154 offset:53248
	ds_read_b128 v[204:207], v154 offset:54272
	ds_read_b128 v[208:211], v154 offset:55296
	ds_read_b128 v[212:215], v154 offset:56320
	global_load_lds_dwordx4 v130, s[72:73]
	s_mov_b32 m0, s42
	s_nop 0
	global_load_lds_dwordx4 v134, s[72:73]
	s_barrier
	s_waitcnt lgkmcnt(0)
	v_mfma_f32_16x16x32_bf16 v[62:65], v[142:145], v[164:167], v[62:65]
	v_mfma_f32_16x16x32_bf16 v[58:61], v[156:159], v[164:167], v[58:61]
	v_mfma_f32_16x16x32_bf16 v[46:49], v[142:145], v[172:175], v[46:49]
	v_mfma_f32_16x16x32_bf16 v[42:45], v[156:159], v[172:175], v[42:45]
	v_mfma_f32_16x16x32_bf16 v[30:33], v[142:145], v[180:183], v[30:33]
	v_mfma_f32_16x16x32_bf16 v[26:29], v[156:159], v[180:183], v[26:29]
	v_mfma_f32_16x16x32_bf16 v[14:17], v[142:145], v[208:211], v[14:17]
	v_mfma_f32_16x16x32_bf16 v[10:13], v[156:159], v[208:211], v[10:13]
	v_mfma_f32_16x16x32_bf16 v[62:65], v[146:149], v[168:171], v[62:65]
	v_mfma_f32_16x16x32_bf16 v[58:61], v[160:163], v[168:171], v[58:61]
	v_mfma_f32_16x16x32_bf16 v[46:49], v[146:149], v[176:179], v[46:49]
	v_mfma_f32_16x16x32_bf16 v[42:45], v[160:163], v[176:179], v[42:45]
	v_mfma_f32_16x16x32_bf16 v[30:33], v[146:149], v[204:207], v[30:33]
	v_mfma_f32_16x16x32_bf16 v[26:29], v[160:163], v[204:207], v[26:29]
	v_mfma_f32_16x16x32_bf16 v[14:17], v[146:149], v[212:215], v[14:17]
	v_mfma_f32_16x16x32_bf16 v[10:13], v[160:163], v[212:215], v[10:13]
	s_barrier
	s_add_i32 s4, s4, s25
	s_mov_b32 m0, s4
	s_nop 0
	global_load_lds_dwordx4 v132, s[76:77]
	s_add_i32 m0, s4, 0x2000
	s_nop 0
	global_load_lds_dwordx4 v136, s[76:77]
	s_add_u32 s0, s0, 0x100
	s_addc_u32 s1, s1, 0
	s_add_u32 s49, s49, 0x100
	s_addc_u32 s65, s65, 0
	s_cmp_ge_u32 s66, s35
	s_mov_b32 s4, s66
	s_waitcnt vmcnt(6)
	s_barrier
	v_mfma_f32_16x16x32_bf16 v[54:57], v[216:219], v[164:167], v[54:57]
	v_mfma_f32_16x16x32_bf16 v[50:53], v[224:227], v[164:167], v[50:53]
	v_mfma_f32_16x16x32_bf16 v[38:41], v[216:219], v[172:175], v[38:41]
	v_mfma_f32_16x16x32_bf16 v[34:37], v[224:227], v[172:175], v[34:37]
	v_mfma_f32_16x16x32_bf16 v[22:25], v[216:219], v[180:183], v[22:25]
	v_mfma_f32_16x16x32_bf16 v[18:21], v[224:227], v[180:183], v[18:21]
	v_mfma_f32_16x16x32_bf16 v[6:9], v[216:219], v[208:211], v[6:9]
	v_mfma_f32_16x16x32_bf16 v[2:5], v[224:227], v[208:211], v[2:5]
	v_mfma_f32_16x16x32_bf16 v[54:57], v[220:223], v[168:171], v[54:57]
	v_mfma_f32_16x16x32_bf16 v[50:53], v[228:231], v[168:171], v[50:53]
	v_mfma_f32_16x16x32_bf16 v[38:41], v[220:223], v[176:179], v[38:41]
	v_mfma_f32_16x16x32_bf16 v[34:37], v[228:231], v[176:179], v[34:37]
	v_mfma_f32_16x16x32_bf16 v[22:25], v[220:223], v[204:207], v[22:25]
	v_mfma_f32_16x16x32_bf16 v[18:21], v[228:231], v[204:207], v[18:21]
	v_mfma_f32_16x16x32_bf16 v[6:9], v[220:223], v[212:215], v[6:9]
	v_mfma_f32_16x16x32_bf16 v[2:5], v[228:231], v[212:215], v[2:5]
	s_barrier
	s_cbranch_scc1 .Lkexit_664
.LBB0_664:
	s_add_i32 s66, s4, 2
	s_add_u32 s18, s0, 0x80
	s_addc_u32 s5, s1, 0
	s_add_i32 s68, 0, 0x10000
	v_add_u32_e32 v150, s68, v153
	ds_read_b128 v[142:145], v150
	ds_read_b128 v[146:149], v150 offset:1024
	ds_read_b128 v[156:159], v150 offset:2048
	ds_read_b128 v[160:163], v150 offset:3072
	s_cmp_eq_u32 s43, s4
	s_cselect_b32 s4, s10, s18
	s_cselect_b32 s5, s11, s5
	s_cselect_b32 s19, s13, s65
	s_cselect_b32 s18, s12, s49
	v_lshl_add_u64 v[150:151], s[0:1], 0, v[138:139]
	s_add_i32 m0, s28, 0xc000
	ds_read_b128 v[164:167], v154
	ds_read_b128 v[168:171], v154 offset:1024
	ds_read_b128 v[172:175], v154 offset:2048
	ds_read_b128 v[176:179], v154 offset:3072
	ds_read_b128 v[180:183], v154 offset:4096
	ds_read_b128 v[204:207], v154 offset:5120
	ds_read_b128 v[208:211], v154 offset:6144
	ds_read_b128 v[212:215], v154 offset:7168
	global_load_lds_dwordx4 v[150:151], off
	v_lshl_add_u64 v[150:151], s[0:1], 0, v[140:141]
	s_add_i32 m0, s28, 0xe000
	s_nop 0
	global_load_lds_dwordx4 v[150:151], off
	s_waitcnt lgkmcnt(8)
	s_barrier
	s_waitcnt lgkmcnt(0)
	v_mfma_f32_16x16x32_bf16 v[126:129], v[142:145], v[164:167], v[126:129]
	v_mfma_f32_16x16x32_bf16 v[122:125], v[156:159], v[164:167], v[122:125]
	v_mfma_f32_16x16x32_bf16 v[110:113], v[142:145], v[172:175], v[110:113]
	v_mfma_f32_16x16x32_bf16 v[106:109], v[156:159], v[172:175], v[106:109]
	v_mfma_f32_16x16x32_bf16 v[94:97], v[142:145], v[180:183], v[94:97]
	v_mfma_f32_16x16x32_bf16 v[90:93], v[156:159], v[180:183], v[90:93]
	v_mfma_f32_16x16x32_bf16 v[78:81], v[142:145], v[208:211], v[78:81]
	v_mfma_f32_16x16x32_bf16 v[74:77], v[156:159], v[208:211], v[74:77]
	v_mfma_f32_16x16x32_bf16 v[126:129], v[146:149], v[168:171], v[126:129]
	v_mfma_f32_16x16x32_bf16 v[122:125], v[160:163], v[168:171], v[122:125]
	v_mfma_f32_16x16x32_bf16 v[110:113], v[146:149], v[176:179], v[110:113]
	v_mfma_f32_16x16x32_bf16 v[106:109], v[160:163], v[176:179], v[106:109]
	v_mfma_f32_16x16x32_bf16 v[94:97], v[146:149], v[204:207], v[94:97]
	v_mfma_f32_16x16x32_bf16 v[90:93], v[160:163], v[204:207], v[90:93]
	v_mfma_f32_16x16x32_bf16 v[78:81], v[146:149], v[212:215], v[78:81]
	v_mfma_f32_16x16x32_bf16 v[74:77], v[160:163], v[212:215], v[74:77]
	s_barrier
	s_add_i32 s69, 0, 0x14000
	v_add_u32_e32 v150, s69, v153
	s_add_i32 s68, s68, s25
	ds_read_b128 v[216:219], v150
	ds_read_b128 v[220:223], v150 offset:1024
	ds_read_b128 v[224:227], v150 offset:2048
	ds_read_b128 v[228:231], v150 offset:3072
	s_add_u32 s70, s18, s6
	s_addc_u32 s71, s19, s7
	s_mov_b32 m0, s68
	s_nop 0
	global_load_lds_dwordx4 v132, s[18:19]
	s_add_i32 m0, s68, 0x2000
	s_nop 0
	global_load_lds_dwordx4 v136, s[18:19]
	s_barrier
	s_waitcnt lgkmcnt(0)
	v_mfma_f32_16x16x32_bf16 v[118:121], v[216:219], v[164:167], v[118:121]
	v_mfma_f32_16x16x32_bf16 v[114:117], v[224:227], v[164:167], v[114:117]
	v_mfma_f32_16x16x32_bf16 v[102:105], v[216:219], v[172:175], v[102:105]
	v_mfma_f32_16x16x32_bf16 v[98:101], v[224:227], v[172:175], v[98:101]
	v_mfma_f32_16x16x32_bf16 v[86:89], v[216:219], v[180:183], v[86:89]
	v_mfma_f32_16x16x32_bf16 v[82:85], v[224:227], v[180:183], v[82:85]
	v_mfma_f32_16x16x32_bf16 v[70:73], v[216:219], v[208:211], v[70:73]
	v_mfma_f32_16x16x32_bf16 v[66:69], v[224:227], v[208:211], v[66:69]
	v_mfma_f32_16x16x32_bf16 v[118:121], v[220:223], v[168:171], v[118:121]
	v_mfma_f32_16x16x32_bf16 v[114:117], v[228:231], v[168:171], v[114:117]
	v_mfma_f32_16x16x32_bf16 v[102:105], v[220:223], v[176:179], v[102:105]
	v_mfma_f32_16x16x32_bf16 v[98:101], v[228:231], v[176:179], v[98:101]
	v_mfma_f32_16x16x32_bf16 v[86:89], v[220:223], v[204:207], v[86:89]
	v_mfma_f32_16x16x32_bf16 v[82:85], v[228:231], v[204:207], v[82:85]
	v_mfma_f32_16x16x32_bf16 v[70:73], v[220:223], v[212:215], v[70:73]
	v_mfma_f32_16x16x32_bf16 v[66:69], v[228:231], v[212:215], v[66:69]
	s_barrier
	s_mov_b32 m0, s28
	s_add_u32 s72, s4, s6
	s_addc_u32 s73, s5, s7
	ds_read_b128 v[164:167], v154 offset:16384
	ds_read_b128 v[168:171], v154 offset:17408
	ds_read_b128 v[172:175], v154 offset:18432
	ds_read_b128 v[176:179], v154 offset:19456
	ds_read_b128 v[180:183], v154 offset:20480
	ds_read_b128 v[204:207], v154 offset:21504
	ds_read_b128 v[208:211], v154 offset:22528
	ds_read_b128 v[212:215], v154 offset:23552
	global_load_lds_dwordx4 v130, s[4:5]
	s_mov_b32 m0, s29
	s_nop 0
	global_load_lds_dwordx4 v134, s[4:5]
	s_barrier
	s_waitcnt lgkmcnt(0)
	v_mfma_f32_16x16x32_bf16 v[62:65], v[142:145], v[164:167], v[62:65]
	v_mfma_f32_16x16x32_bf16 v[58:61], v[156:159], v[164:167], v[58:61]
	v_mfma_f32_16x16x32_bf16 v[46:49], v[142:145], v[172:175], v[46:49]
	v_mfma_f32_16x16x32_bf16 v[42:45], v[156:159], v[172:175], v[42:45]
	v_mfma_f32_16x16x32_bf16 v[30:33], v[142:145], v[180:183], v[30:33]
	v_mfma_f32_16x16x32_bf16 v[26:29], v[156:159], v[180:183], v[26:29]
	v_mfma_f32_16x16x32_bf16 v[14:17], v[142:145], v[208:211], v[14:17]
	v_mfma_f32_16x16x32_bf16 v[10:13], v[156:159], v[208:211], v[10:13]
	v_mfma_f32_16x16x32_bf16 v[62:65], v[146:149], v[168:171], v[62:65]
	v_mfma_f32_16x16x32_bf16 v[58:61], v[160:163], v[168:171], v[58:61]
	v_mfma_f32_16x16x32_bf16 v[46:49], v[146:149], v[176:179], v[46:49]
	v_mfma_f32_16x16x32_bf16 v[42:45], v[160:163], v[176:179], v[42:45]
	v_mfma_f32_16x16x32_bf16 v[30:33], v[146:149], v[204:207], v[30:33]
	v_mfma_f32_16x16x32_bf16 v[26:29], v[160:163], v[204:207], v[26:29]
	v_mfma_f32_16x16x32_bf16 v[14:17], v[146:149], v[212:215], v[14:17]
	v_mfma_f32_16x16x32_bf16 v[10:13], v[160:163], v[212:215], v[10:13]
	s_barrier
	s_add_u32 s18, s18, s14
	s_addc_u32 s19, s19, 0
	s_add_i32 s68, s69, s25
	s_add_u32 s76, s18, s6
	s_addc_u32 s77, s19, s7
	s_mov_b32 m0, s68
	s_nop 0
	global_load_lds_dwordx4 v132, s[18:19]
	s_add_i32 m0, s68, 0x2000
	s_nop 0
	global_load_lds_dwordx4 v136, s[18:19]
	s_waitcnt vmcnt(6)
	s_barrier
	v_mfma_f32_16x16x32_bf16 v[54:57], v[216:219], v[164:167], v[54:57]
	v_mfma_f32_16x16x32_bf16 v[50:53], v[224:227], v[164:167], v[50:53]
	v_mfma_f32_16x16x32_bf16 v[38:41], v[216:219], v[172:175], v[38:41]
	v_mfma_f32_16x16x32_bf16 v[34:37], v[224:227], v[172:175], v[34:37]
	v_mfma_f32_16x16x32_bf16 v[22:25], v[216:219], v[180:183], v[22:25]
	v_mfma_f32_16x16x32_bf16 v[18:21], v[224:227], v[180:183], v[18:21]
	v_mfma_f32_16x16x32_bf16 v[6:9], v[216:219], v[208:211], v[6:9]
	v_mfma_f32_16x16x32_bf16 v[2:5], v[224:227], v[208:211], v[2:5]
	v_mfma_f32_16x16x32_bf16 v[54:57], v[220:223], v[168:171], v[54:57]
	v_mfma_f32_16x16x32_bf16 v[50:53], v[228:231], v[168:171], v[50:53]
	v_mfma_f32_16x16x32_bf16 v[38:41], v[220:223], v[176:179], v[38:41]
	v_mfma_f32_16x16x32_bf16 v[34:37], v[228:231], v[176:179], v[34:37]
	v_mfma_f32_16x16x32_bf16 v[22:25], v[220:223], v[204:207], v[22:25]
	v_mfma_f32_16x16x32_bf16 v[18:21], v[228:231], v[204:207], v[18:21]
	v_mfma_f32_16x16x32_bf16 v[6:9], v[220:223], v[212:215], v[6:9]
	v_mfma_f32_16x16x32_bf16 v[2:5], v[228:231], v[212:215], v[2:5]
	s_barrier
	s_add_i32 s18, 0, 0x18000
	v_add_u32_e32 v155, s18, v153
	ds_read_b128 v[142:145], v155
	ds_read_b128 v[146:149], v155 offset:1024
	ds_read_b128 v[156:159], v155 offset:2048
	ds_read_b128 v[160:163], v155 offset:3072
	s_add_u32 s4, s4, s14
	s_addc_u32 s5, s5, 0
	s_mov_b32 m0, s31
	ds_read_b128 v[164:167], v154 offset:32768
	ds_read_b128 v[168:171], v154 offset:33792
	ds_read_b128 v[172:175], v154 offset:34816
	ds_read_b128 v[176:179], v154 offset:35840
	ds_read_b128 v[180:183], v154 offset:36864
	ds_read_b128 v[204:207], v154 offset:37888
	ds_read_b128 v[208:211], v154 offset:38912
	ds_read_b128 v[212:215], v154 offset:39936
	global_load_lds_dwordx4 v130, s[4:5]
	s_mov_b32 m0, s34
	s_nop 0
	global_load_lds_dwordx4 v134, s[4:5]
	s_waitcnt lgkmcnt(8)
	s_barrier
	s_waitcnt lgkmcnt(0)
	v_mfma_f32_16x16x32_bf16 v[126:129], v[142:145], v[164:167], v[126:129]
	v_mfma_f32_16x16x32_bf16 v[122:125], v[156:159], v[164:167], v[122:125]
	v_mfma_f32_16x16x32_bf16 v[110:113], v[142:145], v[172:175], v[110:113]
	v_mfma_f32_16x16x32_bf16 v[106:109], v[156:159], v[172:175], v[106:109]
	v_mfma_f32_16x16x32_bf16 v[94:97], v[142:145], v[180:183], v[94:97]
	v_mfma_f32_16x16x32_bf16 v[90:93], v[156:159], v[180:183], v[90:93]
	v_mfma_f32_16x16x32_bf16 v[78:81], v[142:145], v[208:211], v[78:81]
	v_mfma_f32_16x16x32_bf16 v[74:77], v[156:159], v[208:211], v[74:77]
	v_mfma_f32_16x16x32_bf16 v[126:129], v[146:149], v[168:171], v[126:129]
	v_mfma_f32_16x16x32_bf16 v[122:125], v[160:163], v[168:171], v[122:125]
	v_mfma_f32_16x16x32_bf16 v[110:113], v[146:149], v[176:179], v[110:113]
	v_mfma_f32_16x16x32_bf16 v[106:109], v[160:163], v[176:179], v[106:109]
	v_mfma_f32_16x16x32_bf16 v[94:97], v[146:149], v[204:207], v[94:97]
	v_mfma_f32_16x16x32_bf16 v[90:93], v[160:163], v[204:207], v[90:93]
	v_mfma_f32_16x16x32_bf16 v[78:81], v[146:149], v[212:215], v[78:81]
	v_mfma_f32_16x16x32_bf16 v[74:77], v[160:163], v[212:215], v[74:77]
	s_barrier
	s_add_i32 s4, 0, 0x1c000
	s_add_i32 s5, s18, s25
	v_add_u32_e32 v155, s4, v153
	s_mov_b32 m0, s5
	ds_read_b128 v[216:219], v155
	ds_read_b128 v[220:223], v155 offset:1024
	ds_read_b128 v[224:227], v155 offset:2048
	ds_read_b128 v[228:231], v155 offset:3072
	global_load_lds_dwordx4 v132, s[70:71]
	s_add_i32 m0, s5, 0x2000
	s_nop 0
	global_load_lds_dwordx4 v136, s[70:71]
	s_barrier
	s_waitcnt lgkmcnt(0)
	v_mfma_f32_16x16x32_bf16 v[118:121], v[216:219], v[164:167], v[118:121]
	v_mfma_f32_16x16x32_bf16 v[114:117], v[224:227], v[164:167], v[114:117]
	v_mfma_f32_16x16x32_bf16 v[102:105], v[216:219], v[172:175], v[102:105]
	v_mfma_f32_16x16x32_bf16 v[98:101], v[224:227], v[172:175], v[98:101]
	v_mfma_f32_16x16x32_bf16 v[86:89], v[216:219], v[180:183], v[86:89]
	v_mfma_f32_16x16x32_bf16 v[82:85], v[224:227], v[180:183], v[82:85]
	v_mfma_f32_16x16x32_bf16 v[70:73], v[216:219], v[208:211], v[70:73]
	v_mfma_f32_16x16x32_bf16 v[66:69], v[224:227], v[208:211], v[66:69]
	v_mfma_f32_16x16x32_bf16 v[118:121], v[220:223], v[168:171], v[118:121]
	v_mfma_f32_16x16x32_bf16 v[114:117], v[228:231], v[168:171], v[114:117]
	v_mfma_f32_16x16x32_bf16 v[102:105], v[220:223], v[176:179], v[102:105]
	v_mfma_f32_16x16x32_bf16 v[98:101], v[228:231], v[176:179], v[98:101]
	v_mfma_f32_16x16x32_bf16 v[86:89], v[220:223], v[204:207], v[86:89]
	v_mfma_f32_16x16x32_bf16 v[82:85], v[228:231], v[204:207], v[82:85]
	v_mfma_f32_16x16x32_bf16 v[70:73], v[220:223], v[212:215], v[70:73]
	v_mfma_f32_16x16x32_bf16 v[66:69], v[228:231], v[212:215], v[66:69]
	s_barrier
	s_mov_b32 m0, s41
	ds_read_b128 v[164:167], v154 offset:49152
	ds_read_b128 v[168:171], v154 offset:50176
	ds_read_b128 v[172:175], v154 offset:51200
	ds_read_b128 v[176:179], v154 offset:52224
	ds_read_b128 v[180:183], v154 offset:53248
	ds_read_b128 v[204:207], v154 offset:54272
	ds_read_b128 v[208:211], v154 offset:55296
	ds_read_b128 v[212:215], v154 offset:56320
	global_load_lds_dwordx4 v130, s[72:73]
	s_mov_b32 m0, s42
	s_nop 0
	global_load_lds_dwordx4 v134, s[72:73]
	s_barrier
	s_waitcnt lgkmcnt(0)
	v_mfma_f32_16x16x32_bf16 v[62:65], v[142:145], v[164:167], v[62:65]
	v_mfma_f32_16x16x32_bf16 v[58:61], v[156:159], v[164:167], v[58:61]
	v_mfma_f32_16x16x32_bf16 v[46:49], v[142:145], v[172:175], v[46:49]
	v_mfma_f32_16x16x32_bf16 v[42:45], v[156:159], v[172:175], v[42:45]
	v_mfma_f32_16x16x32_bf16 v[30:33], v[142:145], v[180:183], v[30:33]
	v_mfma_f32_16x16x32_bf16 v[26:29], v[156:159], v[180:183], v[26:29]
	v_mfma_f32_16x16x32_bf16 v[14:17], v[142:145], v[208:211], v[14:17]
	v_mfma_f32_16x16x32_bf16 v[10:13], v[156:159], v[208:211], v[10:13]
	v_mfma_f32_16x16x32_bf16 v[62:65], v[146:149], v[168:171], v[62:65]
	v_mfma_f32_16x16x32_bf16 v[58:61], v[160:163], v[168:171], v[58:61]
	v_mfma_f32_16x16x32_bf16 v[46:49], v[146:149], v[176:179], v[46:49]
	v_mfma_f32_16x16x32_bf16 v[42:45], v[160:163], v[176:179], v[42:45]
	v_mfma_f32_16x16x32_bf16 v[30:33], v[146:149], v[204:207], v[30:33]
	v_mfma_f32_16x16x32_bf16 v[26:29], v[160:163], v[204:207], v[26:29]
	v_mfma_f32_16x16x32_bf16 v[14:17], v[146:149], v[212:215], v[14:17]
	v_mfma_f32_16x16x32_bf16 v[10:13], v[160:163], v[212:215], v[10:13]
	s_barrier
	s_add_i32 s4, s4, s25
	s_mov_b32 m0, s4
	s_nop 0
	global_load_lds_dwordx4 v132, s[76:77]
	s_add_i32 m0, s4, 0x2000
	s_nop 0
	global_load_lds_dwordx4 v136, s[76:77]
	s_add_u32 s0, s0, 0x100
	s_addc_u32 s1, s1, 0
	s_add_u32 s49, s49, 0x100
	s_addc_u32 s65, s65, 0
	s_cmp_ge_u32 s66, s35
	s_mov_b32 s4, s66
	s_waitcnt vmcnt(6)
	s_barrier
	v_mfma_f32_16x16x32_bf16 v[54:57], v[216:219], v[164:167], v[54:57]
	v_mfma_f32_16x16x32_bf16 v[50:53], v[224:227], v[164:167], v[50:53]
	v_mfma_f32_16x16x32_bf16 v[38:41], v[216:219], v[172:175], v[38:41]
	v_mfma_f32_16x16x32_bf16 v[34:37], v[224:227], v[172:175], v[34:37]
	v_mfma_f32_16x16x32_bf16 v[22:25], v[216:219], v[180:183], v[22:25]
	v_mfma_f32_16x16x32_bf16 v[18:21], v[224:227], v[180:183], v[18:21]
	v_mfma_f32_16x16x32_bf16 v[6:9], v[216:219], v[208:211], v[6:9]
	v_mfma_f32_16x16x32_bf16 v[2:5], v[224:227], v[208:211], v[2:5]
	v_mfma_f32_16x16x32_bf16 v[54:57], v[220:223], v[168:171], v[54:57]
	v_mfma_f32_16x16x32_bf16 v[50:53], v[228:231], v[168:171], v[50:53]
	v_mfma_f32_16x16x32_bf16 v[38:41], v[220:223], v[176:179], v[38:41]
	v_mfma_f32_16x16x32_bf16 v[34:37], v[228:231], v[176:179], v[34:37]
	v_mfma_f32_16x16x32_bf16 v[22:25], v[220:223], v[204:207], v[22:25]
	v_mfma_f32_16x16x32_bf16 v[18:21], v[228:231], v[204:207], v[18:21]
	v_mfma_f32_16x16x32_bf16 v[6:9], v[220:223], v[212:215], v[6:9]
	v_mfma_f32_16x16x32_bf16 v[2:5], v[228:231], v[212:215], v[2:5]
	s_barrier
	s_cbranch_scc0 .LBB0_664

.LBB0_697:
	s_add_u32 s0, s0, 0x80
	s_addc_u32 s1, s1, 0
	s_add_u32 s48, s4, 0x100
	s_addc_u32 s49, s5, 0
	s_mov_b32 s4, 0
	s_waitcnt lgkmcnt(0)
	s_waitcnt vmcnt(0)
	s_add_i32 s65, s4, 2
	s_add_u32 s18, s0, 0x80
	s_addc_u32 s5, s1, 0
	s_add_i32 s66, 0, 0x10000
	v_add_u32_e32 v146, s66, v149
	ds_read_b128 v[142:145], v146
	ds_read_b128 v[152:155], v146 offset:1024
	ds_read_b128 v[156:159], v146 offset:2048
	ds_read_b128 v[160:163], v146 offset:3072
	s_cmp_eq_u32 s34, s4
	s_cselect_b32 s4, s10, s18
	s_cselect_b32 s5, s11, s5
	s_cselect_b32 s19, s13, s49
	s_cselect_b32 s18, s12, s48
	v_lshl_add_u64 v[146:147], s[0:1], 0, v[138:139]
	s_add_i32 m0, s22, 0xc000
	ds_read_b128 v[164:167], v150
	ds_read_b128 v[168:171], v150 offset:1024
	ds_read_b128 v[172:175], v150 offset:2048
	ds_read_b128 v[176:179], v150 offset:3072
	ds_read_b128 v[180:183], v150 offset:4096
	ds_read_b128 v[204:207], v150 offset:5120
	ds_read_b128 v[208:211], v150 offset:6144
	ds_read_b128 v[212:215], v150 offset:7168
	global_load_lds_dwordx4 v[146:147], off
	v_lshl_add_u64 v[146:147], s[0:1], 0, v[140:141]
	s_add_i32 m0, s22, 0xe000
	s_nop 0
	global_load_lds_dwordx4 v[146:147], off
	s_waitcnt lgkmcnt(8)
	s_barrier
	s_waitcnt lgkmcnt(0)
	v_mfma_f32_16x16x32_bf16 v[126:129], v[142:145], v[164:167], 0
	v_mfma_f32_16x16x32_bf16 v[122:125], v[156:159], v[164:167], 0
	v_mfma_f32_16x16x32_bf16 v[110:113], v[142:145], v[172:175], 0
	v_mfma_f32_16x16x32_bf16 v[106:109], v[156:159], v[172:175], 0
	v_mfma_f32_16x16x32_bf16 v[94:97], v[142:145], v[180:183], 0
	v_mfma_f32_16x16x32_bf16 v[90:93], v[156:159], v[180:183], 0
	v_mfma_f32_16x16x32_bf16 v[78:81], v[142:145], v[208:211], 0
	v_mfma_f32_16x16x32_bf16 v[74:77], v[156:159], v[208:211], 0
	v_mfma_f32_16x16x32_bf16 v[126:129], v[152:155], v[168:171], v[126:129]
	v_mfma_f32_16x16x32_bf16 v[122:125], v[160:163], v[168:171], v[122:125]
	v_mfma_f32_16x16x32_bf16 v[110:113], v[152:155], v[176:179], v[110:113]
	v_mfma_f32_16x16x32_bf16 v[106:109], v[160:163], v[176:179], v[106:109]
	v_mfma_f32_16x16x32_bf16 v[94:97], v[152:155], v[204:207], v[94:97]
	v_mfma_f32_16x16x32_bf16 v[90:93], v[160:163], v[204:207], v[90:93]
	v_mfma_f32_16x16x32_bf16 v[78:81], v[152:155], v[212:215], v[78:81]
	v_mfma_f32_16x16x32_bf16 v[74:77], v[160:163], v[212:215], v[74:77]
	s_barrier
	s_add_i32 s67, 0, 0x14000
	v_add_u32_e32 v146, s67, v149
	s_add_i32 s66, s66, s21
	ds_read_b128 v[216:219], v146
	ds_read_b128 v[220:223], v146 offset:1024
	ds_read_b128 v[224:227], v146 offset:2048
	ds_read_b128 v[228:231], v146 offset:3072
	s_add_u32 s70, s18, s6
	s_addc_u32 s71, s19, s7
	s_mov_b32 m0, s66
	s_nop 0
	global_load_lds_dwordx4 v132, s[18:19]
	s_add_i32 m0, s66, 0x2000
	s_nop 0
	global_load_lds_dwordx4 v136, s[18:19]
	s_barrier
	s_waitcnt lgkmcnt(0)
	v_mfma_f32_16x16x32_bf16 v[118:121], v[216:219], v[164:167], 0
	v_mfma_f32_16x16x32_bf16 v[114:117], v[224:227], v[164:167], 0
	v_mfma_f32_16x16x32_bf16 v[102:105], v[216:219], v[172:175], 0
	v_mfma_f32_16x16x32_bf16 v[98:101], v[224:227], v[172:175], 0
	v_mfma_f32_16x16x32_bf16 v[86:89], v[216:219], v[180:183], 0
	v_mfma_f32_16x16x32_bf16 v[82:85], v[224:227], v[180:183], 0
	v_mfma_f32_16x16x32_bf16 v[70:73], v[216:219], v[208:211], 0
	v_mfma_f32_16x16x32_bf16 v[66:69], v[224:227], v[208:211], 0
	v_mfma_f32_16x16x32_bf16 v[118:121], v[220:223], v[168:171], v[118:121]
	v_mfma_f32_16x16x32_bf16 v[114:117], v[228:231], v[168:171], v[114:117]
	v_mfma_f32_16x16x32_bf16 v[102:105], v[220:223], v[176:179], v[102:105]
	v_mfma_f32_16x16x32_bf16 v[98:101], v[228:231], v[176:179], v[98:101]
	v_mfma_f32_16x16x32_bf16 v[86:89], v[220:223], v[204:207], v[86:89]
	v_mfma_f32_16x16x32_bf16 v[82:85], v[228:231], v[204:207], v[82:85]
	v_mfma_f32_16x16x32_bf16 v[70:73], v[220:223], v[212:215], v[70:73]
	v_mfma_f32_16x16x32_bf16 v[66:69], v[228:231], v[212:215], v[66:69]
	s_barrier
	s_mov_b32 m0, s22
	s_add_u32 s72, s4, s6
	s_addc_u32 s73, s5, s7
	ds_read_b128 v[164:167], v150 offset:16384
	ds_read_b128 v[168:171], v150 offset:17408
	ds_read_b128 v[172:175], v150 offset:18432
	ds_read_b128 v[176:179], v150 offset:19456
	ds_read_b128 v[180:183], v150 offset:20480
	ds_read_b128 v[204:207], v150 offset:21504
	ds_read_b128 v[208:211], v150 offset:22528
	ds_read_b128 v[212:215], v150 offset:23552
	global_load_lds_dwordx4 v130, s[4:5]
	s_mov_b32 m0, s23
	s_nop 0
	global_load_lds_dwordx4 v134, s[4:5]
	s_barrier
	s_waitcnt lgkmcnt(0)
	v_mfma_f32_16x16x32_bf16 v[62:65], v[142:145], v[164:167], 0
	v_mfma_f32_16x16x32_bf16 v[58:61], v[156:159], v[164:167], 0
	v_mfma_f32_16x16x32_bf16 v[46:49], v[142:145], v[172:175], 0
	v_mfma_f32_16x16x32_bf16 v[42:45], v[156:159], v[172:175], 0
	v_mfma_f32_16x16x32_bf16 v[30:33], v[142:145], v[180:183], 0
	v_mfma_f32_16x16x32_bf16 v[26:29], v[156:159], v[180:183], 0
	v_mfma_f32_16x16x32_bf16 v[14:17], v[142:145], v[208:211], 0
	v_mfma_f32_16x16x32_bf16 v[10:13], v[156:159], v[208:211], 0
	v_mfma_f32_16x16x32_bf16 v[62:65], v[152:155], v[168:171], v[62:65]
	v_mfma_f32_16x16x32_bf16 v[58:61], v[160:163], v[168:171], v[58:61]
	v_mfma_f32_16x16x32_bf16 v[46:49], v[152:155], v[176:179], v[46:49]
	v_mfma_f32_16x16x32_bf16 v[42:45], v[160:163], v[176:179], v[42:45]
	v_mfma_f32_16x16x32_bf16 v[30:33], v[152:155], v[204:207], v[30:33]
	v_mfma_f32_16x16x32_bf16 v[26:29], v[160:163], v[204:207], v[26:29]
	v_mfma_f32_16x16x32_bf16 v[14:17], v[152:155], v[212:215], v[14:17]
	v_mfma_f32_16x16x32_bf16 v[10:13], v[160:163], v[212:215], v[10:13]
	s_barrier
	s_add_u32 s18, s18, s2
	s_addc_u32 s19, s19, 0
	s_add_i32 s66, s67, s21
	s_add_u32 s76, s18, s6
	s_addc_u32 s77, s19, s7
	s_mov_b32 m0, s66
	s_nop 0
	global_load_lds_dwordx4 v132, s[18:19]
	s_add_i32 m0, s66, 0x2000
	s_nop 0
	global_load_lds_dwordx4 v136, s[18:19]
	s_waitcnt vmcnt(6)
	s_barrier
	v_mfma_f32_16x16x32_bf16 v[54:57], v[216:219], v[164:167], 0
	v_mfma_f32_16x16x32_bf16 v[50:53], v[224:227], v[164:167], 0
	v_mfma_f32_16x16x32_bf16 v[38:41], v[216:219], v[172:175], 0
	v_mfma_f32_16x16x32_bf16 v[34:37], v[224:227], v[172:175], 0
	v_mfma_f32_16x16x32_bf16 v[22:25], v[216:219], v[180:183], 0
	v_mfma_f32_16x16x32_bf16 v[18:21], v[224:227], v[180:183], 0
	v_mfma_f32_16x16x32_bf16 v[6:9], v[216:219], v[208:211], 0
	v_mfma_f32_16x16x32_bf16 v[2:5], v[224:227], v[208:211], 0
	v_mfma_f32_16x16x32_bf16 v[54:57], v[220:223], v[168:171], v[54:57]
	v_mfma_f32_16x16x32_bf16 v[50:53], v[228:231], v[168:171], v[50:53]
	v_mfma_f32_16x16x32_bf16 v[38:41], v[220:223], v[176:179], v[38:41]
	v_mfma_f32_16x16x32_bf16 v[34:37], v[228:231], v[176:179], v[34:37]
	v_mfma_f32_16x16x32_bf16 v[22:25], v[220:223], v[204:207], v[22:25]
	v_mfma_f32_16x16x32_bf16 v[18:21], v[228:231], v[204:207], v[18:21]
	v_mfma_f32_16x16x32_bf16 v[6:9], v[220:223], v[212:215], v[6:9]
	v_mfma_f32_16x16x32_bf16 v[2:5], v[228:231], v[212:215], v[2:5]
	s_barrier
	s_add_i32 s18, 0, 0x18000
	v_add_u32_e32 v151, s18, v149
	ds_read_b128 v[142:145], v151
	ds_read_b128 v[152:155], v151 offset:1024
	ds_read_b128 v[156:159], v151 offset:2048
	ds_read_b128 v[160:163], v151 offset:3072
	s_add_u32 s4, s4, s2
	s_addc_u32 s5, s5, 0
	s_mov_b32 m0, s24
	ds_read_b128 v[164:167], v150 offset:32768
	ds_read_b128 v[168:171], v150 offset:33792
	ds_read_b128 v[172:175], v150 offset:34816
	ds_read_b128 v[176:179], v150 offset:35840
	ds_read_b128 v[180:183], v150 offset:36864
	ds_read_b128 v[204:207], v150 offset:37888
	ds_read_b128 v[208:211], v150 offset:38912
	ds_read_b128 v[212:215], v150 offset:39936
	global_load_lds_dwordx4 v130, s[4:5]
	s_mov_b32 m0, s25
	s_nop 0
	global_load_lds_dwordx4 v134, s[4:5]
	s_waitcnt lgkmcnt(8)
	s_barrier
	s_waitcnt lgkmcnt(0)
	v_mfma_f32_16x16x32_bf16 v[126:129], v[142:145], v[164:167], v[126:129]
	v_mfma_f32_16x16x32_bf16 v[122:125], v[156:159], v[164:167], v[122:125]
	v_mfma_f32_16x16x32_bf16 v[110:113], v[142:145], v[172:175], v[110:113]
	v_mfma_f32_16x16x32_bf16 v[106:109], v[156:159], v[172:175], v[106:109]
	v_mfma_f32_16x16x32_bf16 v[94:97], v[142:145], v[180:183], v[94:97]
	v_mfma_f32_16x16x32_bf16 v[90:93], v[156:159], v[180:183], v[90:93]
	v_mfma_f32_16x16x32_bf16 v[78:81], v[142:145], v[208:211], v[78:81]
	v_mfma_f32_16x16x32_bf16 v[74:77], v[156:159], v[208:211], v[74:77]
	v_mfma_f32_16x16x32_bf16 v[126:129], v[152:155], v[168:171], v[126:129]
	v_mfma_f32_16x16x32_bf16 v[122:125], v[160:163], v[168:171], v[122:125]
	v_mfma_f32_16x16x32_bf16 v[110:113], v[152:155], v[176:179], v[110:113]
	v_mfma_f32_16x16x32_bf16 v[106:109], v[160:163], v[176:179], v[106:109]
	v_mfma_f32_16x16x32_bf16 v[94:97], v[152:155], v[204:207], v[94:97]
	v_mfma_f32_16x16x32_bf16 v[90:93], v[160:163], v[204:207], v[90:93]
	v_mfma_f32_16x16x32_bf16 v[78:81], v[152:155], v[212:215], v[78:81]
	v_mfma_f32_16x16x32_bf16 v[74:77], v[160:163], v[212:215], v[74:77]
	s_barrier
	s_add_i32 s4, 0, 0x1c000
	s_add_i32 s5, s18, s21
	v_add_u32_e32 v151, s4, v149
	s_mov_b32 m0, s5
	ds_read_b128 v[216:219], v151
	ds_read_b128 v[220:223], v151 offset:1024
	ds_read_b128 v[224:227], v151 offset:2048
	ds_read_b128 v[228:231], v151 offset:3072
	global_load_lds_dwordx4 v132, s[70:71]
	s_add_i32 m0, s5, 0x2000
	s_nop 0
	global_load_lds_dwordx4 v136, s[70:71]
	s_barrier
	s_waitcnt lgkmcnt(0)
	v_mfma_f32_16x16x32_bf16 v[118:121], v[216:219], v[164:167], v[118:121]
	v_mfma_f32_16x16x32_bf16 v[114:117], v[224:227], v[164:167], v[114:117]
	v_mfma_f32_16x16x32_bf16 v[102:105], v[216:219], v[172:175], v[102:105]
	v_mfma_f32_16x16x32_bf16 v[98:101], v[224:227], v[172:175], v[98:101]
	v_mfma_f32_16x16x32_bf16 v[86:89], v[216:219], v[180:183], v[86:89]
	v_mfma_f32_16x16x32_bf16 v[82:85], v[224:227], v[180:183], v[82:85]
	v_mfma_f32_16x16x32_bf16 v[70:73], v[216:219], v[208:211], v[70:73]
	v_mfma_f32_16x16x32_bf16 v[66:69], v[224:227], v[208:211], v[66:69]
	v_mfma_f32_16x16x32_bf16 v[118:121], v[220:223], v[168:171], v[118:121]
	v_mfma_f32_16x16x32_bf16 v[114:117], v[228:231], v[168:171], v[114:117]
	v_mfma_f32_16x16x32_bf16 v[102:105], v[220:223], v[176:179], v[102:105]
	v_mfma_f32_16x16x32_bf16 v[98:101], v[228:231], v[176:179], v[98:101]
	v_mfma_f32_16x16x32_bf16 v[86:89], v[220:223], v[204:207], v[86:89]
	v_mfma_f32_16x16x32_bf16 v[82:85], v[228:231], v[204:207], v[82:85]
	v_mfma_f32_16x16x32_bf16 v[70:73], v[220:223], v[212:215], v[70:73]
	v_mfma_f32_16x16x32_bf16 v[66:69], v[228:231], v[212:215], v[66:69]
	s_barrier
	s_mov_b32 m0, s30
	ds_read_b128 v[164:167], v150 offset:49152
	ds_read_b128 v[168:171], v150 offset:50176
	ds_read_b128 v[172:175], v150 offset:51200
	ds_read_b128 v[176:179], v150 offset:52224
	ds_read_b128 v[180:183], v150 offset:53248
	ds_read_b128 v[204:207], v150 offset:54272
	ds_read_b128 v[208:211], v150 offset:55296
	ds_read_b128 v[212:215], v150 offset:56320
	global_load_lds_dwordx4 v130, s[72:73]
	s_mov_b32 m0, s31
	s_nop 0
	global_load_lds_dwordx4 v134, s[72:73]
	s_barrier
	s_waitcnt lgkmcnt(0)
	v_mfma_f32_16x16x32_bf16 v[62:65], v[142:145], v[164:167], v[62:65]
	v_mfma_f32_16x16x32_bf16 v[58:61], v[156:159], v[164:167], v[58:61]
	v_mfma_f32_16x16x32_bf16 v[46:49], v[142:145], v[172:175], v[46:49]
	v_mfma_f32_16x16x32_bf16 v[42:45], v[156:159], v[172:175], v[42:45]
	v_mfma_f32_16x16x32_bf16 v[30:33], v[142:145], v[180:183], v[30:33]
	v_mfma_f32_16x16x32_bf16 v[26:29], v[156:159], v[180:183], v[26:29]
	v_mfma_f32_16x16x32_bf16 v[14:17], v[142:145], v[208:211], v[14:17]
	v_mfma_f32_16x16x32_bf16 v[10:13], v[156:159], v[208:211], v[10:13]
	v_mfma_f32_16x16x32_bf16 v[62:65], v[152:155], v[168:171], v[62:65]
	v_mfma_f32_16x16x32_bf16 v[58:61], v[160:163], v[168:171], v[58:61]
	v_mfma_f32_16x16x32_bf16 v[46:49], v[152:155], v[176:179], v[46:49]
	v_mfma_f32_16x16x32_bf16 v[42:45], v[160:163], v[176:179], v[42:45]
	v_mfma_f32_16x16x32_bf16 v[30:33], v[152:155], v[204:207], v[30:33]
	v_mfma_f32_16x16x32_bf16 v[26:29], v[160:163], v[204:207], v[26:29]
	v_mfma_f32_16x16x32_bf16 v[14:17], v[152:155], v[212:215], v[14:17]
	v_mfma_f32_16x16x32_bf16 v[10:13], v[160:163], v[212:215], v[10:13]
	s_barrier
	s_add_i32 s4, s4, s21
	s_mov_b32 m0, s4
	s_nop 0
	global_load_lds_dwordx4 v132, s[76:77]
	s_add_i32 m0, s4, 0x2000
	s_nop 0
	global_load_lds_dwordx4 v136, s[76:77]
	s_add_u32 s0, s0, 0x100
	s_addc_u32 s1, s1, 0
	s_add_u32 s48, s48, 0x100
	s_addc_u32 s49, s49, 0
	s_cmp_ge_u32 s65, s27
	s_mov_b32 s4, s65
	s_waitcnt vmcnt(6)
	s_barrier
	v_mfma_f32_16x16x32_bf16 v[54:57], v[216:219], v[164:167], v[54:57]
	v_mfma_f32_16x16x32_bf16 v[50:53], v[224:227], v[164:167], v[50:53]
	v_mfma_f32_16x16x32_bf16 v[38:41], v[216:219], v[172:175], v[38:41]
	v_mfma_f32_16x16x32_bf16 v[34:37], v[224:227], v[172:175], v[34:37]
	v_mfma_f32_16x16x32_bf16 v[22:25], v[216:219], v[180:183], v[22:25]
	v_mfma_f32_16x16x32_bf16 v[18:21], v[224:227], v[180:183], v[18:21]
	v_mfma_f32_16x16x32_bf16 v[6:9], v[216:219], v[208:211], v[6:9]
	v_mfma_f32_16x16x32_bf16 v[2:5], v[224:227], v[208:211], v[2:5]
	v_mfma_f32_16x16x32_bf16 v[54:57], v[220:223], v[168:171], v[54:57]
	v_mfma_f32_16x16x32_bf16 v[50:53], v[228:231], v[168:171], v[50:53]
	v_mfma_f32_16x16x32_bf16 v[38:41], v[220:223], v[176:179], v[38:41]
	v_mfma_f32_16x16x32_bf16 v[34:37], v[228:231], v[176:179], v[34:37]
	v_mfma_f32_16x16x32_bf16 v[22:25], v[220:223], v[204:207], v[22:25]
	v_mfma_f32_16x16x32_bf16 v[18:21], v[228:231], v[204:207], v[18:21]
	v_mfma_f32_16x16x32_bf16 v[6:9], v[220:223], v[212:215], v[6:9]
	v_mfma_f32_16x16x32_bf16 v[2:5], v[228:231], v[212:215], v[2:5]
	s_barrier
	s_cbranch_scc1 .Lkexit_698
.LBB0_698:
	s_add_i32 s65, s4, 2
	s_add_u32 s18, s0, 0x80
	s_addc_u32 s5, s1, 0
	s_add_i32 s66, 0, 0x10000
	v_add_u32_e32 v146, s66, v149
	ds_read_b128 v[142:145], v146
	ds_read_b128 v[152:155], v146 offset:1024
	ds_read_b128 v[156:159], v146 offset:2048
	ds_read_b128 v[160:163], v146 offset:3072
	s_cmp_eq_u32 s34, s4
	s_cselect_b32 s4, s10, s18
	s_cselect_b32 s5, s11, s5
	s_cselect_b32 s19, s13, s49
	s_cselect_b32 s18, s12, s48
	v_lshl_add_u64 v[146:147], s[0:1], 0, v[138:139]
	s_add_i32 m0, s22, 0xc000
	ds_read_b128 v[164:167], v150
	ds_read_b128 v[168:171], v150 offset:1024
	ds_read_b128 v[172:175], v150 offset:2048
	ds_read_b128 v[176:179], v150 offset:3072
	ds_read_b128 v[180:183], v150 offset:4096
	ds_read_b128 v[204:207], v150 offset:5120
	ds_read_b128 v[208:211], v150 offset:6144
	ds_read_b128 v[212:215], v150 offset:7168
	global_load_lds_dwordx4 v[146:147], off
	v_lshl_add_u64 v[146:147], s[0:1], 0, v[140:141]
	s_add_i32 m0, s22, 0xe000
	s_nop 0
	global_load_lds_dwordx4 v[146:147], off
	s_waitcnt lgkmcnt(8)
	s_barrier
	s_waitcnt lgkmcnt(0)
	v_mfma_f32_16x16x32_bf16 v[126:129], v[142:145], v[164:167], v[126:129]
	v_mfma_f32_16x16x32_bf16 v[122:125], v[156:159], v[164:167], v[122:125]
	v_mfma_f32_16x16x32_bf16 v[110:113], v[142:145], v[172:175], v[110:113]
	v_mfma_f32_16x16x32_bf16 v[106:109], v[156:159], v[172:175], v[106:109]
	v_mfma_f32_16x16x32_bf16 v[94:97], v[142:145], v[180:183], v[94:97]
	v_mfma_f32_16x16x32_bf16 v[90:93], v[156:159], v[180:183], v[90:93]
	v_mfma_f32_16x16x32_bf16 v[78:81], v[142:145], v[208:211], v[78:81]
	v_mfma_f32_16x16x32_bf16 v[74:77], v[156:159], v[208:211], v[74:77]
	v_mfma_f32_16x16x32_bf16 v[126:129], v[152:155], v[168:171], v[126:129]
	v_mfma_f32_16x16x32_bf16 v[122:125], v[160:163], v[168:171], v[122:125]
	v_mfma_f32_16x16x32_bf16 v[110:113], v[152:155], v[176:179], v[110:113]
	v_mfma_f32_16x16x32_bf16 v[106:109], v[160:163], v[176:179], v[106:109]
	v_mfma_f32_16x16x32_bf16 v[94:97], v[152:155], v[204:207], v[94:97]
	v_mfma_f32_16x16x32_bf16 v[90:93], v[160:163], v[204:207], v[90:93]
	v_mfma_f32_16x16x32_bf16 v[78:81], v[152:155], v[212:215], v[78:81]
	v_mfma_f32_16x16x32_bf16 v[74:77], v[160:163], v[212:215], v[74:77]
	s_barrier
	s_add_i32 s67, 0, 0x14000
	v_add_u32_e32 v146, s67, v149
	s_add_i32 s66, s66, s21
	ds_read_b128 v[216:219], v146
	ds_read_b128 v[220:223], v146 offset:1024
	ds_read_b128 v[224:227], v146 offset:2048
	ds_read_b128 v[228:231], v146 offset:3072
	s_add_u32 s70, s18, s6
	s_addc_u32 s71, s19, s7
	s_mov_b32 m0, s66
	s_nop 0
	global_load_lds_dwordx4 v132, s[18:19]
	s_add_i32 m0, s66, 0x2000
	s_nop 0
	global_load_lds_dwordx4 v136, s[18:19]
	s_barrier
	s_waitcnt lgkmcnt(0)
	v_mfma_f32_16x16x32_bf16 v[118:121], v[216:219], v[164:167], v[118:121]
	v_mfma_f32_16x16x32_bf16 v[114:117], v[224:227], v[164:167], v[114:117]
	v_mfma_f32_16x16x32_bf16 v[102:105], v[216:219], v[172:175], v[102:105]
	v_mfma_f32_16x16x32_bf16 v[98:101], v[224:227], v[172:175], v[98:101]
	v_mfma_f32_16x16x32_bf16 v[86:89], v[216:219], v[180:183], v[86:89]
	v_mfma_f32_16x16x32_bf16 v[82:85], v[224:227], v[180:183], v[82:85]
	v_mfma_f32_16x16x32_bf16 v[70:73], v[216:219], v[208:211], v[70:73]
	v_mfma_f32_16x16x32_bf16 v[66:69], v[224:227], v[208:211], v[66:69]
	v_mfma_f32_16x16x32_bf16 v[118:121], v[220:223], v[168:171], v[118:121]
	v_mfma_f32_16x16x32_bf16 v[114:117], v[228:231], v[168:171], v[114:117]
	v_mfma_f32_16x16x32_bf16 v[102:105], v[220:223], v[176:179], v[102:105]
	v_mfma_f32_16x16x32_bf16 v[98:101], v[228:231], v[176:179], v[98:101]
	v_mfma_f32_16x16x32_bf16 v[86:89], v[220:223], v[204:207], v[86:89]
	v_mfma_f32_16x16x32_bf16 v[82:85], v[228:231], v[204:207], v[82:85]
	v_mfma_f32_16x16x32_bf16 v[70:73], v[220:223], v[212:215], v[70:73]
	v_mfma_f32_16x16x32_bf16 v[66:69], v[228:231], v[212:215], v[66:69]
	s_barrier
	s_mov_b32 m0, s22
	s_add_u32 s72, s4, s6
	s_addc_u32 s73, s5, s7
	ds_read_b128 v[164:167], v150 offset:16384
	ds_read_b128 v[168:171], v150 offset:17408
	ds_read_b128 v[172:175], v150 offset:18432
	ds_read_b128 v[176:179], v150 offset:19456
	ds_read_b128 v[180:183], v150 offset:20480
	ds_read_b128 v[204:207], v150 offset:21504
	ds_read_b128 v[208:211], v150 offset:22528
	ds_read_b128 v[212:215], v150 offset:23552
	global_load_lds_dwordx4 v130, s[4:5]
	s_mov_b32 m0, s23
	s_nop 0
	global_load_lds_dwordx4 v134, s[4:5]
	s_barrier
	s_waitcnt lgkmcnt(0)
	v_mfma_f32_16x16x32_bf16 v[62:65], v[142:145], v[164:167], v[62:65]
	v_mfma_f32_16x16x32_bf16 v[58:61], v[156:159], v[164:167], v[58:61]
	v_mfma_f32_16x16x32_bf16 v[46:49], v[142:145], v[172:175], v[46:49]
	v_mfma_f32_16x16x32_bf16 v[42:45], v[156:159], v[172:175], v[42:45]
	v_mfma_f32_16x16x32_bf16 v[30:33], v[142:145], v[180:183], v[30:33]
	v_mfma_f32_16x16x32_bf16 v[26:29], v[156:159], v[180:183], v[26:29]
	v_mfma_f32_16x16x32_bf16 v[14:17], v[142:145], v[208:211], v[14:17]
	v_mfma_f32_16x16x32_bf16 v[10:13], v[156:159], v[208:211], v[10:13]
	v_mfma_f32_16x16x32_bf16 v[62:65], v[152:155], v[168:171], v[62:65]
	v_mfma_f32_16x16x32_bf16 v[58:61], v[160:163], v[168:171], v[58:61]
	v_mfma_f32_16x16x32_bf16 v[46:49], v[152:155], v[176:179], v[46:49]
	v_mfma_f32_16x16x32_bf16 v[42:45], v[160:163], v[176:179], v[42:45]
	v_mfma_f32_16x16x32_bf16 v[30:33], v[152:155], v[204:207], v[30:33]
	v_mfma_f32_16x16x32_bf16 v[26:29], v[160:163], v[204:207], v[26:29]
	v_mfma_f32_16x16x32_bf16 v[14:17], v[152:155], v[212:215], v[14:17]
	v_mfma_f32_16x16x32_bf16 v[10:13], v[160:163], v[212:215], v[10:13]
	s_barrier
	s_add_u32 s18, s18, s2
	s_addc_u32 s19, s19, 0
	s_add_i32 s66, s67, s21
	s_add_u32 s76, s18, s6
	s_addc_u32 s77, s19, s7
	s_mov_b32 m0, s66
	s_nop 0
	global_load_lds_dwordx4 v132, s[18:19]
	s_add_i32 m0, s66, 0x2000
	s_nop 0
	global_load_lds_dwordx4 v136, s[18:19]
	s_waitcnt vmcnt(6)
	s_barrier
	v_mfma_f32_16x16x32_bf16 v[54:57], v[216:219], v[164:167], v[54:57]
	v_mfma_f32_16x16x32_bf16 v[50:53], v[224:227], v[164:167], v[50:53]
	v_mfma_f32_16x16x32_bf16 v[38:41], v[216:219], v[172:175], v[38:41]
	v_mfma_f32_16x16x32_bf16 v[34:37], v[224:227], v[172:175], v[34:37]
	v_mfma_f32_16x16x32_bf16 v[22:25], v[216:219], v[180:183], v[22:25]
	v_mfma_f32_16x16x32_bf16 v[18:21], v[224:227], v[180:183], v[18:21]
	v_mfma_f32_16x16x32_bf16 v[6:9], v[216:219], v[208:211], v[6:9]
	v_mfma_f32_16x16x32_bf16 v[2:5], v[224:227], v[208:211], v[2:5]
	v_mfma_f32_16x16x32_bf16 v[54:57], v[220:223], v[168:171], v[54:57]
	v_mfma_f32_16x16x32_bf16 v[50:53], v[228:231], v[168:171], v[50:53]
	v_mfma_f32_16x16x32_bf16 v[38:41], v[220:223], v[176:179], v[38:41]
	v_mfma_f32_16x16x32_bf16 v[34:37], v[228:231], v[176:179], v[34:37]
	v_mfma_f32_16x16x32_bf16 v[22:25], v[220:223], v[204:207], v[22:25]
	v_mfma_f32_16x16x32_bf16 v[18:21], v[228:231], v[204:207], v[18:21]
	v_mfma_f32_16x16x32_bf16 v[6:9], v[220:223], v[212:215], v[6:9]
	v_mfma_f32_16x16x32_bf16 v[2:5], v[228:231], v[212:215], v[2:5]
	s_barrier
	s_add_i32 s18, 0, 0x18000
	v_add_u32_e32 v151, s18, v149
	ds_read_b128 v[142:145], v151
	ds_read_b128 v[152:155], v151 offset:1024
	ds_read_b128 v[156:159], v151 offset:2048
	ds_read_b128 v[160:163], v151 offset:3072
	s_add_u32 s4, s4, s2
	s_addc_u32 s5, s5, 0
	s_mov_b32 m0, s24
	ds_read_b128 v[164:167], v150 offset:32768
	ds_read_b128 v[168:171], v150 offset:33792
	ds_read_b128 v[172:175], v150 offset:34816
	ds_read_b128 v[176:179], v150 offset:35840
	ds_read_b128 v[180:183], v150 offset:36864
	ds_read_b128 v[204:207], v150 offset:37888
	ds_read_b128 v[208:211], v150 offset:38912
	ds_read_b128 v[212:215], v150 offset:39936
	global_load_lds_dwordx4 v130, s[4:5]
	s_mov_b32 m0, s25
	s_nop 0
	global_load_lds_dwordx4 v134, s[4:5]
	s_waitcnt lgkmcnt(8)
	s_barrier
	s_waitcnt lgkmcnt(0)
	v_mfma_f32_16x16x32_bf16 v[126:129], v[142:145], v[164:167], v[126:129]
	v_mfma_f32_16x16x32_bf16 v[122:125], v[156:159], v[164:167], v[122:125]
	v_mfma_f32_16x16x32_bf16 v[110:113], v[142:145], v[172:175], v[110:113]
	v_mfma_f32_16x16x32_bf16 v[106:109], v[156:159], v[172:175], v[106:109]
	v_mfma_f32_16x16x32_bf16 v[94:97], v[142:145], v[180:183], v[94:97]
	v_mfma_f32_16x16x32_bf16 v[90:93], v[156:159], v[180:183], v[90:93]
	v_mfma_f32_16x16x32_bf16 v[78:81], v[142:145], v[208:211], v[78:81]
	v_mfma_f32_16x16x32_bf16 v[74:77], v[156:159], v[208:211], v[74:77]
	v_mfma_f32_16x16x32_bf16 v[126:129], v[152:155], v[168:171], v[126:129]
	v_mfma_f32_16x16x32_bf16 v[122:125], v[160:163], v[168:171], v[122:125]
	v_mfma_f32_16x16x32_bf16 v[110:113], v[152:155], v[176:179], v[110:113]
	v_mfma_f32_16x16x32_bf16 v[106:109], v[160:163], v[176:179], v[106:109]
	v_mfma_f32_16x16x32_bf16 v[94:97], v[152:155], v[204:207], v[94:97]
	v_mfma_f32_16x16x32_bf16 v[90:93], v[160:163], v[204:207], v[90:93]
	v_mfma_f32_16x16x32_bf16 v[78:81], v[152:155], v[212:215], v[78:81]
	v_mfma_f32_16x16x32_bf16 v[74:77], v[160:163], v[212:215], v[74:77]
	s_barrier
	s_add_i32 s4, 0, 0x1c000
	s_add_i32 s5, s18, s21
	v_add_u32_e32 v151, s4, v149
	s_mov_b32 m0, s5
	ds_read_b128 v[216:219], v151
	ds_read_b128 v[220:223], v151 offset:1024
	ds_read_b128 v[224:227], v151 offset:2048
	ds_read_b128 v[228:231], v151 offset:3072
	global_load_lds_dwordx4 v132, s[70:71]
	s_add_i32 m0, s5, 0x2000
	s_nop 0
	global_load_lds_dwordx4 v136, s[70:71]
	s_barrier
	s_waitcnt lgkmcnt(0)
	v_mfma_f32_16x16x32_bf16 v[118:121], v[216:219], v[164:167], v[118:121]
	v_mfma_f32_16x16x32_bf16 v[114:117], v[224:227], v[164:167], v[114:117]
	v_mfma_f32_16x16x32_bf16 v[102:105], v[216:219], v[172:175], v[102:105]
	v_mfma_f32_16x16x32_bf16 v[98:101], v[224:227], v[172:175], v[98:101]
	v_mfma_f32_16x16x32_bf16 v[86:89], v[216:219], v[180:183], v[86:89]
	v_mfma_f32_16x16x32_bf16 v[82:85], v[224:227], v[180:183], v[82:85]
	v_mfma_f32_16x16x32_bf16 v[70:73], v[216:219], v[208:211], v[70:73]
	v_mfma_f32_16x16x32_bf16 v[66:69], v[224:227], v[208:211], v[66:69]
	v_mfma_f32_16x16x32_bf16 v[118:121], v[220:223], v[168:171], v[118:121]
	v_mfma_f32_16x16x32_bf16 v[114:117], v[228:231], v[168:171], v[114:117]
	v_mfma_f32_16x16x32_bf16 v[102:105], v[220:223], v[176:179], v[102:105]
	v_mfma_f32_16x16x32_bf16 v[98:101], v[228:231], v[176:179], v[98:101]
	v_mfma_f32_16x16x32_bf16 v[86:89], v[220:223], v[204:207], v[86:89]
	v_mfma_f32_16x16x32_bf16 v[82:85], v[228:231], v[204:207], v[82:85]
	v_mfma_f32_16x16x32_bf16 v[70:73], v[220:223], v[212:215], v[70:73]
	v_mfma_f32_16x16x32_bf16 v[66:69], v[228:231], v[212:215], v[66:69]
	s_barrier
	s_mov_b32 m0, s30
	ds_read_b128 v[164:167], v150 offset:49152
	ds_read_b128 v[168:171], v150 offset:50176
	ds_read_b128 v[172:175], v150 offset:51200
	ds_read_b128 v[176:179], v150 offset:52224
	ds_read_b128 v[180:183], v150 offset:53248
	ds_read_b128 v[204:207], v150 offset:54272
	ds_read_b128 v[208:211], v150 offset:55296
	ds_read_b128 v[212:215], v150 offset:56320
	global_load_lds_dwordx4 v130, s[72:73]
	s_mov_b32 m0, s31
	s_nop 0
	global_load_lds_dwordx4 v134, s[72:73]
	s_barrier
	s_waitcnt lgkmcnt(0)
	v_mfma_f32_16x16x32_bf16 v[62:65], v[142:145], v[164:167], v[62:65]
	v_mfma_f32_16x16x32_bf16 v[58:61], v[156:159], v[164:167], v[58:61]
	v_mfma_f32_16x16x32_bf16 v[46:49], v[142:145], v[172:175], v[46:49]
	v_mfma_f32_16x16x32_bf16 v[42:45], v[156:159], v[172:175], v[42:45]
	v_mfma_f32_16x16x32_bf16 v[30:33], v[142:145], v[180:183], v[30:33]
	v_mfma_f32_16x16x32_bf16 v[26:29], v[156:159], v[180:183], v[26:29]
	v_mfma_f32_16x16x32_bf16 v[14:17], v[142:145], v[208:211], v[14:17]
	v_mfma_f32_16x16x32_bf16 v[10:13], v[156:159], v[208:211], v[10:13]
	v_mfma_f32_16x16x32_bf16 v[62:65], v[152:155], v[168:171], v[62:65]
	v_mfma_f32_16x16x32_bf16 v[58:61], v[160:163], v[168:171], v[58:61]
	v_mfma_f32_16x16x32_bf16 v[46:49], v[152:155], v[176:179], v[46:49]
	v_mfma_f32_16x16x32_bf16 v[42:45], v[160:163], v[176:179], v[42:45]
	v_mfma_f32_16x16x32_bf16 v[30:33], v[152:155], v[204:207], v[30:33]
	v_mfma_f32_16x16x32_bf16 v[26:29], v[160:163], v[204:207], v[26:29]
	v_mfma_f32_16x16x32_bf16 v[14:17], v[152:155], v[212:215], v[14:17]
	v_mfma_f32_16x16x32_bf16 v[10:13], v[160:163], v[212:215], v[10:13]
	s_barrier
	s_add_i32 s4, s4, s21
	s_mov_b32 m0, s4
	s_nop 0
	global_load_lds_dwordx4 v132, s[76:77]
	s_add_i32 m0, s4, 0x2000
	s_nop 0
	global_load_lds_dwordx4 v136, s[76:77]
	s_add_u32 s0, s0, 0x100
	s_addc_u32 s1, s1, 0
	s_add_u32 s48, s48, 0x100
	s_addc_u32 s49, s49, 0
	s_cmp_ge_u32 s65, s27
	s_mov_b32 s4, s65
	s_waitcnt vmcnt(6)
	s_barrier
	v_mfma_f32_16x16x32_bf16 v[54:57], v[216:219], v[164:167], v[54:57]
	v_mfma_f32_16x16x32_bf16 v[50:53], v[224:227], v[164:167], v[50:53]
	v_mfma_f32_16x16x32_bf16 v[38:41], v[216:219], v[172:175], v[38:41]
	v_mfma_f32_16x16x32_bf16 v[34:37], v[224:227], v[172:175], v[34:37]
	v_mfma_f32_16x16x32_bf16 v[22:25], v[216:219], v[180:183], v[22:25]
	v_mfma_f32_16x16x32_bf16 v[18:21], v[224:227], v[180:183], v[18:21]
	v_mfma_f32_16x16x32_bf16 v[6:9], v[216:219], v[208:211], v[6:9]
	v_mfma_f32_16x16x32_bf16 v[2:5], v[224:227], v[208:211], v[2:5]
	v_mfma_f32_16x16x32_bf16 v[54:57], v[220:223], v[168:171], v[54:57]
	v_mfma_f32_16x16x32_bf16 v[50:53], v[228:231], v[168:171], v[50:53]
	v_mfma_f32_16x16x32_bf16 v[38:41], v[220:223], v[176:179], v[38:41]
	v_mfma_f32_16x16x32_bf16 v[34:37], v[228:231], v[176:179], v[34:37]
	v_mfma_f32_16x16x32_bf16 v[22:25], v[220:223], v[204:207], v[22:25]
	v_mfma_f32_16x16x32_bf16 v[18:21], v[228:231], v[204:207], v[18:21]
	v_mfma_f32_16x16x32_bf16 v[6:9], v[220:223], v[212:215], v[6:9]
	v_mfma_f32_16x16x32_bf16 v[2:5], v[228:231], v[212:215], v[2:5]
	s_barrier
	s_cbranch_scc0 .LBB0_698

.LBB0_805:
	s_add_u32 s0, s0, 0x80
	s_addc_u32 s1, s1, 0
	s_add_u32 s12, s4, 0x100
	s_addc_u32 s13, s5, 0
	s_mov_b32 s4, 0
	s_waitcnt vmcnt(0)
	s_add_i32 s27, s4, 2
	s_add_u32 s10, s0, 0x80
	s_addc_u32 s5, s1, 0
	s_add_i32 s28, 0, 0x10000
	v_add_u32_e32 v154, s28, v171
	ds_read_b128 v[142:145], v154
	ds_read_b128 v[146:149], v154 offset:1024
	ds_read_b128 v[150:153], v154 offset:2048
	ds_read_b128 v[154:157], v154 offset:3072
	s_cmp_eq_u32 s48, s4
	s_cselect_b32 s4, s22, s10
	s_cselect_b32 s5, s23, s5
	s_cselect_b32 s11, s25, s13
	s_cselect_b32 s10, s24, s12
	v_lshl_add_u64 v[212:213], s[0:1], 0, v[138:139]
	s_add_i32 m0, s35, 0xc000
	ds_read_b128 v[158:161], v172
	ds_read_b128 v[162:165], v172 offset:1024
	ds_read_b128 v[166:169], v172 offset:2048
	ds_read_b128 v[174:177], v172 offset:3072
	ds_read_b128 v[178:181], v172 offset:4096
	ds_read_b128 v[182:185], v172 offset:5120
	ds_read_b128 v[204:207], v172 offset:6144
	ds_read_b128 v[208:211], v172 offset:7168
	global_load_lds_dwordx4 v[212:213], off
	v_lshl_add_u64 v[212:213], s[0:1], 0, v[140:141]
	s_add_i32 m0, s35, 0xe000
	s_nop 0
	global_load_lds_dwordx4 v[212:213], off
	s_waitcnt lgkmcnt(8)
	s_barrier
	s_waitcnt lgkmcnt(0)
	v_mfma_f32_16x16x32_bf16 v[126:129], v[142:145], v[158:161], 0
	v_mfma_f32_16x16x32_bf16 v[122:125], v[150:153], v[158:161], 0
	v_mfma_f32_16x16x32_bf16 v[110:113], v[142:145], v[166:169], 0
	v_mfma_f32_16x16x32_bf16 v[106:109], v[150:153], v[166:169], 0
	v_mfma_f32_16x16x32_bf16 v[94:97], v[142:145], v[178:181], 0
	v_mfma_f32_16x16x32_bf16 v[90:93], v[150:153], v[178:181], 0
	v_mfma_f32_16x16x32_bf16 v[78:81], v[142:145], v[204:207], 0
	v_mfma_f32_16x16x32_bf16 v[74:77], v[150:153], v[204:207], 0
	v_mfma_f32_16x16x32_bf16 v[126:129], v[146:149], v[162:165], v[126:129]
	v_mfma_f32_16x16x32_bf16 v[122:125], v[154:157], v[162:165], v[122:125]
	v_mfma_f32_16x16x32_bf16 v[110:113], v[146:149], v[174:177], v[110:113]
	v_mfma_f32_16x16x32_bf16 v[106:109], v[154:157], v[174:177], v[106:109]
	v_mfma_f32_16x16x32_bf16 v[94:97], v[146:149], v[182:185], v[94:97]
	v_mfma_f32_16x16x32_bf16 v[90:93], v[154:157], v[182:185], v[90:93]
	v_mfma_f32_16x16x32_bf16 v[78:81], v[146:149], v[208:211], v[78:81]
	v_mfma_f32_16x16x32_bf16 v[74:77], v[154:157], v[208:211], v[74:77]
	s_barrier
	s_add_i32 s29, 0, 0x14000
	s_add_i32 s28, s28, s34
	v_add_u32_e32 v173, s29, v171
	s_add_u32 s78, s10, s6
	s_addc_u32 s79, s11, s7
	s_mov_b32 m0, s28
	ds_read_b128 v[212:215], v173
	ds_read_b128 v[216:219], v173 offset:1024
	ds_read_b128 v[220:223], v173 offset:2048
	ds_read_b128 v[224:227], v173 offset:3072
	global_load_lds_dwordx4 v132, s[10:11]
	s_add_i32 m0, s28, 0x2000
	s_nop 0
	global_load_lds_dwordx4 v136, s[10:11]
	s_barrier
	s_waitcnt lgkmcnt(0)
	v_mfma_f32_16x16x32_bf16 v[118:121], v[212:215], v[158:161], 0
	v_mfma_f32_16x16x32_bf16 v[114:117], v[220:223], v[158:161], 0
	v_mfma_f32_16x16x32_bf16 v[102:105], v[212:215], v[166:169], 0
	v_mfma_f32_16x16x32_bf16 v[98:101], v[220:223], v[166:169], 0
	v_mfma_f32_16x16x32_bf16 v[86:89], v[212:215], v[178:181], 0
	v_mfma_f32_16x16x32_bf16 v[82:85], v[220:223], v[178:181], 0
	v_mfma_f32_16x16x32_bf16 v[70:73], v[212:215], v[204:207], 0
	v_mfma_f32_16x16x32_bf16 v[66:69], v[220:223], v[204:207], 0
	v_mfma_f32_16x16x32_bf16 v[118:121], v[216:219], v[162:165], v[118:121]
	v_mfma_f32_16x16x32_bf16 v[114:117], v[224:227], v[162:165], v[114:117]
	v_mfma_f32_16x16x32_bf16 v[102:105], v[216:219], v[174:177], v[102:105]
	v_mfma_f32_16x16x32_bf16 v[98:101], v[224:227], v[174:177], v[98:101]
	v_mfma_f32_16x16x32_bf16 v[86:89], v[216:219], v[182:185], v[86:89]
	v_mfma_f32_16x16x32_bf16 v[82:85], v[224:227], v[182:185], v[82:85]
	v_mfma_f32_16x16x32_bf16 v[70:73], v[216:219], v[208:211], v[70:73]
	v_mfma_f32_16x16x32_bf16 v[66:69], v[224:227], v[208:211], v[66:69]
	s_barrier
	s_mov_b32 m0, s35
	s_add_u32 s80, s4, s6
	s_addc_u32 s81, s5, s7
	ds_read_b128 v[158:161], v172 offset:16384
	ds_read_b128 v[162:165], v172 offset:17408
	ds_read_b128 v[166:169], v172 offset:18432
	ds_read_b128 v[174:177], v172 offset:19456
	ds_read_b128 v[178:181], v172 offset:20480
	ds_read_b128 v[182:185], v172 offset:21504
	ds_read_b128 v[204:207], v172 offset:22528
	ds_read_b128 v[208:211], v172 offset:23552
	global_load_lds_dwordx4 v130, s[4:5]
	s_mov_b32 m0, s40
	s_nop 0
	global_load_lds_dwordx4 v134, s[4:5]
	s_barrier
	s_waitcnt lgkmcnt(0)
	v_mfma_f32_16x16x32_bf16 v[62:65], v[142:145], v[158:161], 0
	v_mfma_f32_16x16x32_bf16 v[58:61], v[150:153], v[158:161], 0
	v_mfma_f32_16x16x32_bf16 v[46:49], v[142:145], v[166:169], 0
	v_mfma_f32_16x16x32_bf16 v[42:45], v[150:153], v[166:169], 0
	v_mfma_f32_16x16x32_bf16 v[30:33], v[142:145], v[178:181], 0
	v_mfma_f32_16x16x32_bf16 v[26:29], v[150:153], v[178:181], 0
	v_mfma_f32_16x16x32_bf16 v[14:17], v[142:145], v[204:207], 0
	v_mfma_f32_16x16x32_bf16 v[10:13], v[150:153], v[204:207], 0
	v_mfma_f32_16x16x32_bf16 v[62:65], v[146:149], v[162:165], v[62:65]
	v_mfma_f32_16x16x32_bf16 v[58:61], v[154:157], v[162:165], v[58:61]
	v_mfma_f32_16x16x32_bf16 v[46:49], v[146:149], v[174:177], v[46:49]
	v_mfma_f32_16x16x32_bf16 v[42:45], v[154:157], v[174:177], v[42:45]
	v_mfma_f32_16x16x32_bf16 v[30:33], v[146:149], v[182:185], v[30:33]
	v_mfma_f32_16x16x32_bf16 v[26:29], v[154:157], v[182:185], v[26:29]
	v_mfma_f32_16x16x32_bf16 v[14:17], v[146:149], v[208:211], v[14:17]
	v_mfma_f32_16x16x32_bf16 v[10:13], v[154:157], v[208:211], v[10:13]
	s_barrier
	s_add_u32 s10, s10, s92
	s_addc_u32 s11, s11, 0
	s_add_i32 s28, s29, s34
	s_add_u32 s58, s10, s6
	s_addc_u32 s59, s11, s7
	s_mov_b32 m0, s28
	s_nop 0
	global_load_lds_dwordx4 v132, s[10:11]
	s_add_i32 m0, s28, 0x2000
	s_nop 0
	global_load_lds_dwordx4 v136, s[10:11]
	s_waitcnt vmcnt(6)
	s_barrier
	v_mfma_f32_16x16x32_bf16 v[54:57], v[212:215], v[158:161], 0
	v_mfma_f32_16x16x32_bf16 v[50:53], v[220:223], v[158:161], 0
	v_mfma_f32_16x16x32_bf16 v[38:41], v[212:215], v[166:169], 0
	v_mfma_f32_16x16x32_bf16 v[34:37], v[220:223], v[166:169], 0
	v_mfma_f32_16x16x32_bf16 v[22:25], v[212:215], v[178:181], 0
	v_mfma_f32_16x16x32_bf16 v[18:21], v[220:223], v[178:181], 0
	v_mfma_f32_16x16x32_bf16 v[6:9], v[212:215], v[204:207], 0
	v_mfma_f32_16x16x32_bf16 v[2:5], v[220:223], v[204:207], 0
	v_mfma_f32_16x16x32_bf16 v[54:57], v[216:219], v[162:165], v[54:57]
	v_mfma_f32_16x16x32_bf16 v[50:53], v[224:227], v[162:165], v[50:53]
	v_mfma_f32_16x16x32_bf16 v[38:41], v[216:219], v[174:177], v[38:41]
	v_mfma_f32_16x16x32_bf16 v[34:37], v[224:227], v[174:177], v[34:37]
	v_mfma_f32_16x16x32_bf16 v[22:25], v[216:219], v[182:185], v[22:25]
	v_mfma_f32_16x16x32_bf16 v[18:21], v[224:227], v[182:185], v[18:21]
	v_mfma_f32_16x16x32_bf16 v[6:9], v[216:219], v[208:211], v[6:9]
	v_mfma_f32_16x16x32_bf16 v[2:5], v[224:227], v[208:211], v[2:5]
	s_barrier
	s_add_i32 s10, 0, 0x18000
	v_add_u32_e32 v154, s10, v171
	ds_read_b128 v[142:145], v154
	ds_read_b128 v[146:149], v154 offset:1024
	ds_read_b128 v[150:153], v154 offset:2048
	ds_read_b128 v[154:157], v154 offset:3072
	s_add_u32 s4, s4, s92
	s_addc_u32 s5, s5, 0
	s_mov_b32 m0, s41
	ds_read_b128 v[158:161], v172 offset:32768
	ds_read_b128 v[162:165], v172 offset:33792
	ds_read_b128 v[166:169], v172 offset:34816
	ds_read_b128 v[174:177], v172 offset:35840
	ds_read_b128 v[178:181], v172 offset:36864
	ds_read_b128 v[182:185], v172 offset:37888
	ds_read_b128 v[204:207], v172 offset:38912
	ds_read_b128 v[208:211], v172 offset:39936
	global_load_lds_dwordx4 v130, s[4:5]
	s_mov_b32 m0, s42
	s_nop 0
	global_load_lds_dwordx4 v134, s[4:5]
	s_waitcnt lgkmcnt(8)
	s_barrier
	s_waitcnt lgkmcnt(0)
	v_mfma_f32_16x16x32_bf16 v[126:129], v[142:145], v[158:161], v[126:129]
	v_mfma_f32_16x16x32_bf16 v[122:125], v[150:153], v[158:161], v[122:125]
	v_mfma_f32_16x16x32_bf16 v[110:113], v[142:145], v[166:169], v[110:113]
	v_mfma_f32_16x16x32_bf16 v[106:109], v[150:153], v[166:169], v[106:109]
	v_mfma_f32_16x16x32_bf16 v[94:97], v[142:145], v[178:181], v[94:97]
	v_mfma_f32_16x16x32_bf16 v[90:93], v[150:153], v[178:181], v[90:93]
	v_mfma_f32_16x16x32_bf16 v[78:81], v[142:145], v[204:207], v[78:81]
	v_mfma_f32_16x16x32_bf16 v[74:77], v[150:153], v[204:207], v[74:77]
	v_mfma_f32_16x16x32_bf16 v[126:129], v[146:149], v[162:165], v[126:129]
	v_mfma_f32_16x16x32_bf16 v[122:125], v[154:157], v[162:165], v[122:125]
	v_mfma_f32_16x16x32_bf16 v[110:113], v[146:149], v[174:177], v[110:113]
	v_mfma_f32_16x16x32_bf16 v[106:109], v[154:157], v[174:177], v[106:109]
	v_mfma_f32_16x16x32_bf16 v[94:97], v[146:149], v[182:185], v[94:97]
	v_mfma_f32_16x16x32_bf16 v[90:93], v[154:157], v[182:185], v[90:93]
	v_mfma_f32_16x16x32_bf16 v[78:81], v[146:149], v[208:211], v[78:81]
	v_mfma_f32_16x16x32_bf16 v[74:77], v[154:157], v[208:211], v[74:77]
	s_barrier
	s_add_i32 s4, 0, 0x1c000
	s_add_i32 s5, s10, s34
	v_add_u32_e32 v173, s4, v171
	s_mov_b32 m0, s5
	ds_read_b128 v[212:215], v173
	ds_read_b128 v[216:219], v173 offset:1024
	ds_read_b128 v[220:223], v173 offset:2048
	ds_read_b128 v[224:227], v173 offset:3072
	global_load_lds_dwordx4 v132, s[78:79]
	s_add_i32 m0, s5, 0x2000
	s_nop 0
	global_load_lds_dwordx4 v136, s[78:79]
	s_barrier
	s_waitcnt lgkmcnt(0)
	v_mfma_f32_16x16x32_bf16 v[118:121], v[212:215], v[158:161], v[118:121]
	v_mfma_f32_16x16x32_bf16 v[114:117], v[220:223], v[158:161], v[114:117]
	v_mfma_f32_16x16x32_bf16 v[102:105], v[212:215], v[166:169], v[102:105]
	v_mfma_f32_16x16x32_bf16 v[98:101], v[220:223], v[166:169], v[98:101]
	v_mfma_f32_16x16x32_bf16 v[86:89], v[212:215], v[178:181], v[86:89]
	v_mfma_f32_16x16x32_bf16 v[82:85], v[220:223], v[178:181], v[82:85]
	v_mfma_f32_16x16x32_bf16 v[70:73], v[212:215], v[204:207], v[70:73]
	v_mfma_f32_16x16x32_bf16 v[66:69], v[220:223], v[204:207], v[66:69]
	v_mfma_f32_16x16x32_bf16 v[118:121], v[216:219], v[162:165], v[118:121]
	v_mfma_f32_16x16x32_bf16 v[114:117], v[224:227], v[162:165], v[114:117]
	v_mfma_f32_16x16x32_bf16 v[102:105], v[216:219], v[174:177], v[102:105]
	v_mfma_f32_16x16x32_bf16 v[98:101], v[224:227], v[174:177], v[98:101]
	v_mfma_f32_16x16x32_bf16 v[86:89], v[216:219], v[182:185], v[86:89]
	v_mfma_f32_16x16x32_bf16 v[82:85], v[224:227], v[182:185], v[82:85]
	v_mfma_f32_16x16x32_bf16 v[70:73], v[216:219], v[208:211], v[70:73]
	v_mfma_f32_16x16x32_bf16 v[66:69], v[224:227], v[208:211], v[66:69]
	s_barrier
	s_mov_b32 m0, s46
	ds_read_b128 v[158:161], v172 offset:49152
	ds_read_b128 v[162:165], v172 offset:50176
	ds_read_b128 v[166:169], v172 offset:51200
	ds_read_b128 v[174:177], v172 offset:52224
	ds_read_b128 v[178:181], v172 offset:53248
	ds_read_b128 v[182:185], v172 offset:54272
	ds_read_b128 v[204:207], v172 offset:55296
	ds_read_b128 v[208:211], v172 offset:56320
	global_load_lds_dwordx4 v130, s[80:81]
	s_mov_b32 m0, s47
	s_nop 0
	global_load_lds_dwordx4 v134, s[80:81]
	s_barrier
	s_waitcnt lgkmcnt(0)
	v_mfma_f32_16x16x32_bf16 v[62:65], v[142:145], v[158:161], v[62:65]
	v_mfma_f32_16x16x32_bf16 v[58:61], v[150:153], v[158:161], v[58:61]
	v_mfma_f32_16x16x32_bf16 v[46:49], v[142:145], v[166:169], v[46:49]
	v_mfma_f32_16x16x32_bf16 v[42:45], v[150:153], v[166:169], v[42:45]
	v_mfma_f32_16x16x32_bf16 v[30:33], v[142:145], v[178:181], v[30:33]
	v_mfma_f32_16x16x32_bf16 v[26:29], v[150:153], v[178:181], v[26:29]
	v_mfma_f32_16x16x32_bf16 v[14:17], v[142:145], v[204:207], v[14:17]
	v_mfma_f32_16x16x32_bf16 v[10:13], v[150:153], v[204:207], v[10:13]
	v_mfma_f32_16x16x32_bf16 v[62:65], v[146:149], v[162:165], v[62:65]
	v_mfma_f32_16x16x32_bf16 v[58:61], v[154:157], v[162:165], v[58:61]
	v_mfma_f32_16x16x32_bf16 v[46:49], v[146:149], v[174:177], v[46:49]
	v_mfma_f32_16x16x32_bf16 v[42:45], v[154:157], v[174:177], v[42:45]
	v_mfma_f32_16x16x32_bf16 v[30:33], v[146:149], v[182:185], v[30:33]
	v_mfma_f32_16x16x32_bf16 v[26:29], v[154:157], v[182:185], v[26:29]
	v_mfma_f32_16x16x32_bf16 v[14:17], v[146:149], v[208:211], v[14:17]
	v_mfma_f32_16x16x32_bf16 v[10:13], v[154:157], v[208:211], v[10:13]
	s_barrier
	s_add_i32 s4, s4, s34
	s_mov_b32 m0, s4
	s_nop 0
	global_load_lds_dwordx4 v132, s[58:59]
	s_add_i32 m0, s4, 0x2000
	s_nop 0
	global_load_lds_dwordx4 v136, s[58:59]
	s_add_u32 s0, s0, 0x100
	s_addc_u32 s1, s1, 0
	s_add_u32 s12, s12, 0x100
	s_addc_u32 s13, s13, 0
	s_cmp_ge_u32 s27, s43
	s_mov_b32 s4, s27
	s_waitcnt vmcnt(6)
	s_barrier
	v_mfma_f32_16x16x32_bf16 v[54:57], v[212:215], v[158:161], v[54:57]
	v_mfma_f32_16x16x32_bf16 v[50:53], v[220:223], v[158:161], v[50:53]
	v_mfma_f32_16x16x32_bf16 v[38:41], v[212:215], v[166:169], v[38:41]
	v_mfma_f32_16x16x32_bf16 v[34:37], v[220:223], v[166:169], v[34:37]
	v_mfma_f32_16x16x32_bf16 v[22:25], v[212:215], v[178:181], v[22:25]
	v_mfma_f32_16x16x32_bf16 v[18:21], v[220:223], v[178:181], v[18:21]
	v_mfma_f32_16x16x32_bf16 v[6:9], v[212:215], v[204:207], v[6:9]
	v_mfma_f32_16x16x32_bf16 v[2:5], v[220:223], v[204:207], v[2:5]
	v_mfma_f32_16x16x32_bf16 v[54:57], v[216:219], v[162:165], v[54:57]
	v_mfma_f32_16x16x32_bf16 v[50:53], v[224:227], v[162:165], v[50:53]
	v_mfma_f32_16x16x32_bf16 v[38:41], v[216:219], v[174:177], v[38:41]
	v_mfma_f32_16x16x32_bf16 v[34:37], v[224:227], v[174:177], v[34:37]
	v_mfma_f32_16x16x32_bf16 v[22:25], v[216:219], v[182:185], v[22:25]
	v_mfma_f32_16x16x32_bf16 v[18:21], v[224:227], v[182:185], v[18:21]
	v_mfma_f32_16x16x32_bf16 v[6:9], v[216:219], v[208:211], v[6:9]
	v_mfma_f32_16x16x32_bf16 v[2:5], v[224:227], v[208:211], v[2:5]
	s_barrier
	s_cbranch_scc1 .Lkexit_806
.LBB0_806:
	s_add_i32 s27, s4, 2
	s_add_u32 s10, s0, 0x80
	s_addc_u32 s5, s1, 0
	s_add_i32 s28, 0, 0x10000
	v_add_u32_e32 v154, s28, v171
	ds_read_b128 v[142:145], v154
	ds_read_b128 v[146:149], v154 offset:1024
	ds_read_b128 v[150:153], v154 offset:2048
	ds_read_b128 v[154:157], v154 offset:3072
	s_cmp_eq_u32 s48, s4
	s_cselect_b32 s4, s22, s10
	s_cselect_b32 s5, s23, s5
	s_cselect_b32 s11, s25, s13
	s_cselect_b32 s10, s24, s12
	v_lshl_add_u64 v[212:213], s[0:1], 0, v[138:139]
	s_add_i32 m0, s35, 0xc000
	ds_read_b128 v[158:161], v172
	ds_read_b128 v[162:165], v172 offset:1024
	ds_read_b128 v[166:169], v172 offset:2048
	ds_read_b128 v[174:177], v172 offset:3072
	ds_read_b128 v[178:181], v172 offset:4096
	ds_read_b128 v[182:185], v172 offset:5120
	ds_read_b128 v[204:207], v172 offset:6144
	ds_read_b128 v[208:211], v172 offset:7168
	global_load_lds_dwordx4 v[212:213], off
	v_lshl_add_u64 v[212:213], s[0:1], 0, v[140:141]
	s_add_i32 m0, s35, 0xe000
	s_nop 0
	global_load_lds_dwordx4 v[212:213], off
	s_waitcnt lgkmcnt(8)
	s_barrier
	s_waitcnt lgkmcnt(0)
	v_mfma_f32_16x16x32_bf16 v[126:129], v[142:145], v[158:161], v[126:129]
	v_mfma_f32_16x16x32_bf16 v[122:125], v[150:153], v[158:161], v[122:125]
	v_mfma_f32_16x16x32_bf16 v[110:113], v[142:145], v[166:169], v[110:113]
	v_mfma_f32_16x16x32_bf16 v[106:109], v[150:153], v[166:169], v[106:109]
	v_mfma_f32_16x16x32_bf16 v[94:97], v[142:145], v[178:181], v[94:97]
	v_mfma_f32_16x16x32_bf16 v[90:93], v[150:153], v[178:181], v[90:93]
	v_mfma_f32_16x16x32_bf16 v[78:81], v[142:145], v[204:207], v[78:81]
	v_mfma_f32_16x16x32_bf16 v[74:77], v[150:153], v[204:207], v[74:77]
	v_mfma_f32_16x16x32_bf16 v[126:129], v[146:149], v[162:165], v[126:129]
	v_mfma_f32_16x16x32_bf16 v[122:125], v[154:157], v[162:165], v[122:125]
	v_mfma_f32_16x16x32_bf16 v[110:113], v[146:149], v[174:177], v[110:113]
	v_mfma_f32_16x16x32_bf16 v[106:109], v[154:157], v[174:177], v[106:109]
	v_mfma_f32_16x16x32_bf16 v[94:97], v[146:149], v[182:185], v[94:97]
	v_mfma_f32_16x16x32_bf16 v[90:93], v[154:157], v[182:185], v[90:93]
	v_mfma_f32_16x16x32_bf16 v[78:81], v[146:149], v[208:211], v[78:81]
	v_mfma_f32_16x16x32_bf16 v[74:77], v[154:157], v[208:211], v[74:77]
	s_barrier
	s_add_i32 s29, 0, 0x14000
	s_add_i32 s28, s28, s34
	v_add_u32_e32 v173, s29, v171
	s_add_u32 s78, s10, s6
	s_addc_u32 s79, s11, s7
	s_mov_b32 m0, s28
	ds_read_b128 v[212:215], v173
	ds_read_b128 v[216:219], v173 offset:1024
	ds_read_b128 v[220:223], v173 offset:2048
	ds_read_b128 v[224:227], v173 offset:3072
	global_load_lds_dwordx4 v132, s[10:11]
	s_add_i32 m0, s28, 0x2000
	s_nop 0
	global_load_lds_dwordx4 v136, s[10:11]
	s_barrier
	s_waitcnt lgkmcnt(0)
	v_mfma_f32_16x16x32_bf16 v[118:121], v[212:215], v[158:161], v[118:121]
	v_mfma_f32_16x16x32_bf16 v[114:117], v[220:223], v[158:161], v[114:117]
	v_mfma_f32_16x16x32_bf16 v[102:105], v[212:215], v[166:169], v[102:105]
	v_mfma_f32_16x16x32_bf16 v[98:101], v[220:223], v[166:169], v[98:101]
	v_mfma_f32_16x16x32_bf16 v[86:89], v[212:215], v[178:181], v[86:89]
	v_mfma_f32_16x16x32_bf16 v[82:85], v[220:223], v[178:181], v[82:85]
	v_mfma_f32_16x16x32_bf16 v[70:73], v[212:215], v[204:207], v[70:73]
	v_mfma_f32_16x16x32_bf16 v[66:69], v[220:223], v[204:207], v[66:69]
	v_mfma_f32_16x16x32_bf16 v[118:121], v[216:219], v[162:165], v[118:121]
	v_mfma_f32_16x16x32_bf16 v[114:117], v[224:227], v[162:165], v[114:117]
	v_mfma_f32_16x16x32_bf16 v[102:105], v[216:219], v[174:177], v[102:105]
	v_mfma_f32_16x16x32_bf16 v[98:101], v[224:227], v[174:177], v[98:101]
	v_mfma_f32_16x16x32_bf16 v[86:89], v[216:219], v[182:185], v[86:89]
	v_mfma_f32_16x16x32_bf16 v[82:85], v[224:227], v[182:185], v[82:85]
	v_mfma_f32_16x16x32_bf16 v[70:73], v[216:219], v[208:211], v[70:73]
	v_mfma_f32_16x16x32_bf16 v[66:69], v[224:227], v[208:211], v[66:69]
	s_barrier
	s_mov_b32 m0, s35
	s_add_u32 s80, s4, s6
	s_addc_u32 s81, s5, s7
	ds_read_b128 v[158:161], v172 offset:16384
	ds_read_b128 v[162:165], v172 offset:17408
	ds_read_b128 v[166:169], v172 offset:18432
	ds_read_b128 v[174:177], v172 offset:19456
	ds_read_b128 v[178:181], v172 offset:20480
	ds_read_b128 v[182:185], v172 offset:21504
	ds_read_b128 v[204:207], v172 offset:22528
	ds_read_b128 v[208:211], v172 offset:23552
	global_load_lds_dwordx4 v130, s[4:5]
	s_mov_b32 m0, s40
	s_nop 0
	global_load_lds_dwordx4 v134, s[4:5]
	s_barrier
	s_waitcnt lgkmcnt(0)
	v_mfma_f32_16x16x32_bf16 v[62:65], v[142:145], v[158:161], v[62:65]
	v_mfma_f32_16x16x32_bf16 v[58:61], v[150:153], v[158:161], v[58:61]
	v_mfma_f32_16x16x32_bf16 v[46:49], v[142:145], v[166:169], v[46:49]
	v_mfma_f32_16x16x32_bf16 v[42:45], v[150:153], v[166:169], v[42:45]
	v_mfma_f32_16x16x32_bf16 v[30:33], v[142:145], v[178:181], v[30:33]
	v_mfma_f32_16x16x32_bf16 v[26:29], v[150:153], v[178:181], v[26:29]
	v_mfma_f32_16x16x32_bf16 v[14:17], v[142:145], v[204:207], v[14:17]
	v_mfma_f32_16x16x32_bf16 v[10:13], v[150:153], v[204:207], v[10:13]
	v_mfma_f32_16x16x32_bf16 v[62:65], v[146:149], v[162:165], v[62:65]
	v_mfma_f32_16x16x32_bf16 v[58:61], v[154:157], v[162:165], v[58:61]
	v_mfma_f32_16x16x32_bf16 v[46:49], v[146:149], v[174:177], v[46:49]
	v_mfma_f32_16x16x32_bf16 v[42:45], v[154:157], v[174:177], v[42:45]
	v_mfma_f32_16x16x32_bf16 v[30:33], v[146:149], v[182:185], v[30:33]
	v_mfma_f32_16x16x32_bf16 v[26:29], v[154:157], v[182:185], v[26:29]
	v_mfma_f32_16x16x32_bf16 v[14:17], v[146:149], v[208:211], v[14:17]
	v_mfma_f32_16x16x32_bf16 v[10:13], v[154:157], v[208:211], v[10:13]
	s_barrier
	s_add_u32 s10, s10, s92
	s_addc_u32 s11, s11, 0
	s_add_i32 s28, s29, s34
	s_add_u32 s58, s10, s6
	s_addc_u32 s59, s11, s7
	s_mov_b32 m0, s28
	s_nop 0
	global_load_lds_dwordx4 v132, s[10:11]
	s_add_i32 m0, s28, 0x2000
	s_nop 0
	global_load_lds_dwordx4 v136, s[10:11]
	s_waitcnt vmcnt(6)
	s_barrier
	v_mfma_f32_16x16x32_bf16 v[54:57], v[212:215], v[158:161], v[54:57]
	v_mfma_f32_16x16x32_bf16 v[50:53], v[220:223], v[158:161], v[50:53]
	v_mfma_f32_16x16x32_bf16 v[38:41], v[212:215], v[166:169], v[38:41]
	v_mfma_f32_16x16x32_bf16 v[34:37], v[220:223], v[166:169], v[34:37]
	v_mfma_f32_16x16x32_bf16 v[22:25], v[212:215], v[178:181], v[22:25]
	v_mfma_f32_16x16x32_bf16 v[18:21], v[220:223], v[178:181], v[18:21]
	v_mfma_f32_16x16x32_bf16 v[6:9], v[212:215], v[204:207], v[6:9]
	v_mfma_f32_16x16x32_bf16 v[2:5], v[220:223], v[204:207], v[2:5]
	v_mfma_f32_16x16x32_bf16 v[54:57], v[216:219], v[162:165], v[54:57]
	v_mfma_f32_16x16x32_bf16 v[50:53], v[224:227], v[162:165], v[50:53]
	v_mfma_f32_16x16x32_bf16 v[38:41], v[216:219], v[174:177], v[38:41]
	v_mfma_f32_16x16x32_bf16 v[34:37], v[224:227], v[174:177], v[34:37]
	v_mfma_f32_16x16x32_bf16 v[22:25], v[216:219], v[182:185], v[22:25]
	v_mfma_f32_16x16x32_bf16 v[18:21], v[224:227], v[182:185], v[18:21]
	v_mfma_f32_16x16x32_bf16 v[6:9], v[216:219], v[208:211], v[6:9]
	v_mfma_f32_16x16x32_bf16 v[2:5], v[224:227], v[208:211], v[2:5]
	s_barrier
	s_add_i32 s10, 0, 0x18000
	v_add_u32_e32 v154, s10, v171
	ds_read_b128 v[142:145], v154
	ds_read_b128 v[146:149], v154 offset:1024
	ds_read_b128 v[150:153], v154 offset:2048
	ds_read_b128 v[154:157], v154 offset:3072
	s_add_u32 s4, s4, s92
	s_addc_u32 s5, s5, 0
	s_mov_b32 m0, s41
	ds_read_b128 v[158:161], v172 offset:32768
	ds_read_b128 v[162:165], v172 offset:33792
	ds_read_b128 v[166:169], v172 offset:34816
	ds_read_b128 v[174:177], v172 offset:35840
	ds_read_b128 v[178:181], v172 offset:36864
	ds_read_b128 v[182:185], v172 offset:37888
	ds_read_b128 v[204:207], v172 offset:38912
	ds_read_b128 v[208:211], v172 offset:39936
	global_load_lds_dwordx4 v130, s[4:5]
	s_mov_b32 m0, s42
	s_nop 0
	global_load_lds_dwordx4 v134, s[4:5]
	s_waitcnt lgkmcnt(8)
	s_barrier
	s_waitcnt lgkmcnt(0)
	v_mfma_f32_16x16x32_bf16 v[126:129], v[142:145], v[158:161], v[126:129]
	v_mfma_f32_16x16x32_bf16 v[122:125], v[150:153], v[158:161], v[122:125]
	v_mfma_f32_16x16x32_bf16 v[110:113], v[142:145], v[166:169], v[110:113]
	v_mfma_f32_16x16x32_bf16 v[106:109], v[150:153], v[166:169], v[106:109]
	v_mfma_f32_16x16x32_bf16 v[94:97], v[142:145], v[178:181], v[94:97]
	v_mfma_f32_16x16x32_bf16 v[90:93], v[150:153], v[178:181], v[90:93]
	v_mfma_f32_16x16x32_bf16 v[78:81], v[142:145], v[204:207], v[78:81]
	v_mfma_f32_16x16x32_bf16 v[74:77], v[150:153], v[204:207], v[74:77]
	v_mfma_f32_16x16x32_bf16 v[126:129], v[146:149], v[162:165], v[126:129]
	v_mfma_f32_16x16x32_bf16 v[122:125], v[154:157], v[162:165], v[122:125]
	v_mfma_f32_16x16x32_bf16 v[110:113], v[146:149], v[174:177], v[110:113]
	v_mfma_f32_16x16x32_bf16 v[106:109], v[154:157], v[174:177], v[106:109]
	v_mfma_f32_16x16x32_bf16 v[94:97], v[146:149], v[182:185], v[94:97]
	v_mfma_f32_16x16x32_bf16 v[90:93], v[154:157], v[182:185], v[90:93]
	v_mfma_f32_16x16x32_bf16 v[78:81], v[146:149], v[208:211], v[78:81]
	v_mfma_f32_16x16x32_bf16 v[74:77], v[154:157], v[208:211], v[74:77]
	s_barrier
	s_add_i32 s4, 0, 0x1c000
	s_add_i32 s5, s10, s34
	v_add_u32_e32 v173, s4, v171
	s_mov_b32 m0, s5
	ds_read_b128 v[212:215], v173
	ds_read_b128 v[216:219], v173 offset:1024
	ds_read_b128 v[220:223], v173 offset:2048
	ds_read_b128 v[224:227], v173 offset:3072
	global_load_lds_dwordx4 v132, s[78:79]
	s_add_i32 m0, s5, 0x2000
	s_nop 0
	global_load_lds_dwordx4 v136, s[78:79]
	s_barrier
	s_waitcnt lgkmcnt(0)
	v_mfma_f32_16x16x32_bf16 v[118:121], v[212:215], v[158:161], v[118:121]
	v_mfma_f32_16x16x32_bf16 v[114:117], v[220:223], v[158:161], v[114:117]
	v_mfma_f32_16x16x32_bf16 v[102:105], v[212:215], v[166:169], v[102:105]
	v_mfma_f32_16x16x32_bf16 v[98:101], v[220:223], v[166:169], v[98:101]
	v_mfma_f32_16x16x32_bf16 v[86:89], v[212:215], v[178:181], v[86:89]
	v_mfma_f32_16x16x32_bf16 v[82:85], v[220:223], v[178:181], v[82:85]
	v_mfma_f32_16x16x32_bf16 v[70:73], v[212:215], v[204:207], v[70:73]
	v_mfma_f32_16x16x32_bf16 v[66:69], v[220:223], v[204:207], v[66:69]
	v_mfma_f32_16x16x32_bf16 v[118:121], v[216:219], v[162:165], v[118:121]
	v_mfma_f32_16x16x32_bf16 v[114:117], v[224:227], v[162:165], v[114:117]
	v_mfma_f32_16x16x32_bf16 v[102:105], v[216:219], v[174:177], v[102:105]
	v_mfma_f32_16x16x32_bf16 v[98:101], v[224:227], v[174:177], v[98:101]
	v_mfma_f32_16x16x32_bf16 v[86:89], v[216:219], v[182:185], v[86:89]
	v_mfma_f32_16x16x32_bf16 v[82:85], v[224:227], v[182:185], v[82:85]
	v_mfma_f32_16x16x32_bf16 v[70:73], v[216:219], v[208:211], v[70:73]
	v_mfma_f32_16x16x32_bf16 v[66:69], v[224:227], v[208:211], v[66:69]
	s_barrier
	s_mov_b32 m0, s46
	ds_read_b128 v[158:161], v172 offset:49152
	ds_read_b128 v[162:165], v172 offset:50176
	ds_read_b128 v[166:169], v172 offset:51200
	ds_read_b128 v[174:177], v172 offset:52224
	ds_read_b128 v[178:181], v172 offset:53248
	ds_read_b128 v[182:185], v172 offset:54272
	ds_read_b128 v[204:207], v172 offset:55296
	ds_read_b128 v[208:211], v172 offset:56320
	global_load_lds_dwordx4 v130, s[80:81]
	s_mov_b32 m0, s47
	s_nop 0
	global_load_lds_dwordx4 v134, s[80:81]
	s_barrier
	s_waitcnt lgkmcnt(0)
	v_mfma_f32_16x16x32_bf16 v[62:65], v[142:145], v[158:161], v[62:65]
	v_mfma_f32_16x16x32_bf16 v[58:61], v[150:153], v[158:161], v[58:61]
	v_mfma_f32_16x16x32_bf16 v[46:49], v[142:145], v[166:169], v[46:49]
	v_mfma_f32_16x16x32_bf16 v[42:45], v[150:153], v[166:169], v[42:45]
	v_mfma_f32_16x16x32_bf16 v[30:33], v[142:145], v[178:181], v[30:33]
	v_mfma_f32_16x16x32_bf16 v[26:29], v[150:153], v[178:181], v[26:29]
	v_mfma_f32_16x16x32_bf16 v[14:17], v[142:145], v[204:207], v[14:17]
	v_mfma_f32_16x16x32_bf16 v[10:13], v[150:153], v[204:207], v[10:13]
	v_mfma_f32_16x16x32_bf16 v[62:65], v[146:149], v[162:165], v[62:65]
	v_mfma_f32_16x16x32_bf16 v[58:61], v[154:157], v[162:165], v[58:61]
	v_mfma_f32_16x16x32_bf16 v[46:49], v[146:149], v[174:177], v[46:49]
	v_mfma_f32_16x16x32_bf16 v[42:45], v[154:157], v[174:177], v[42:45]
	v_mfma_f32_16x16x32_bf16 v[30:33], v[146:149], v[182:185], v[30:33]
	v_mfma_f32_16x16x32_bf16 v[26:29], v[154:157], v[182:185], v[26:29]
	v_mfma_f32_16x16x32_bf16 v[14:17], v[146:149], v[208:211], v[14:17]
	v_mfma_f32_16x16x32_bf16 v[10:13], v[154:157], v[208:211], v[10:13]
	s_barrier
	s_add_i32 s4, s4, s34
	s_mov_b32 m0, s4
	s_nop 0
	global_load_lds_dwordx4 v132, s[58:59]
	s_add_i32 m0, s4, 0x2000
	s_nop 0
	global_load_lds_dwordx4 v136, s[58:59]
	s_add_u32 s0, s0, 0x100
	s_addc_u32 s1, s1, 0
	s_add_u32 s12, s12, 0x100
	s_addc_u32 s13, s13, 0
	s_cmp_ge_u32 s27, s43
	s_mov_b32 s4, s27
	s_waitcnt vmcnt(6)
	s_barrier
	v_mfma_f32_16x16x32_bf16 v[54:57], v[212:215], v[158:161], v[54:57]
	v_mfma_f32_16x16x32_bf16 v[50:53], v[220:223], v[158:161], v[50:53]
	v_mfma_f32_16x16x32_bf16 v[38:41], v[212:215], v[166:169], v[38:41]
	v_mfma_f32_16x16x32_bf16 v[34:37], v[220:223], v[166:169], v[34:37]
	v_mfma_f32_16x16x32_bf16 v[22:25], v[212:215], v[178:181], v[22:25]
	v_mfma_f32_16x16x32_bf16 v[18:21], v[220:223], v[178:181], v[18:21]
	v_mfma_f32_16x16x32_bf16 v[6:9], v[212:215], v[204:207], v[6:9]
	v_mfma_f32_16x16x32_bf16 v[2:5], v[220:223], v[204:207], v[2:5]
	v_mfma_f32_16x16x32_bf16 v[54:57], v[216:219], v[162:165], v[54:57]
	v_mfma_f32_16x16x32_bf16 v[50:53], v[224:227], v[162:165], v[50:53]
	v_mfma_f32_16x16x32_bf16 v[38:41], v[216:219], v[174:177], v[38:41]
	v_mfma_f32_16x16x32_bf16 v[34:37], v[224:227], v[174:177], v[34:37]
	v_mfma_f32_16x16x32_bf16 v[22:25], v[216:219], v[182:185], v[22:25]
	v_mfma_f32_16x16x32_bf16 v[18:21], v[224:227], v[182:185], v[18:21]
	v_mfma_f32_16x16x32_bf16 v[6:9], v[216:219], v[208:211], v[6:9]
	v_mfma_f32_16x16x32_bf16 v[2:5], v[224:227], v[208:211], v[2:5]
	s_barrier
	s_cbranch_scc0 .LBB0_806
